# GEMM K-loops: each wave reaches the barrier closing its MFMA block two MFMAs early and issues the last two at raised priority (barrier count and memory-op order unchanged)
# speedup vs baseline: 1.0025x; 1.0025x over previous
; #define PG8_STAGE(bufoff, gbase, voff) do { _Pragma("unroll") for (int _i = 0; _i < 2; ++_i) \
;         __builtin_amdgcn_global_load_lds((const unsigned*)((const char*)(gbase) + (voff)[_i]), (PG8_LAS unsigned*)(lds + (bufoff) + ldsw + _i * 8192), 16, 0, 0); } while (0)
; #define PG8_LDA(dst, b, h) do { _Pragma("unroll") for (int m = 0; m < 4; ++m) _Pragma("unroll") for (int k = 0; k < 2; ++k) dst[m][k] = *(const PG8_LAS bf16x8*)(lds + PG8_SA(b, h) + aoff + m * 2048 + k * 1024); } while (0)
; #define PG8_LDB(dst, b, h) do { _Pragma("unroll") for (int n = 0; n < 2; ++n) _Pragma("unroll") for (int k = 0; k < 2; ++k) dst[n][k] = *(const PG8_LAS bf16x8*)(lds + PG8_SB(b, h) + boff + n * 2048 + k * 1024); } while (0)
; #define PG8_WAIT_V(n) asm volatile("s_waitcnt vmcnt(" #n ")" ::: "memory")
; #define PG8_WAIT_L(n) asm volatile("s_waitcnt lgkmcnt(" #n ")" ::: "memory")
; #define PG8_BAR __builtin_amdgcn_s_barrier()
; template <class Epi, class Sched, bool ALIGN_EPI = false, bool SP2 = false>
; __device__ __forceinline__ void gemm_phase(PG8_LAS unsigned char* lds, const Gemm g, const Sched& S, const Epi& E) {
;     ...
;         for (int th = 0; th < (Epi::HAS_MID ? 2 : 1); ++th) { const int tlo = Epi::HAS_MID ? th * (nt / 2) : 0, thi = Epi::HAS_MID ? tlo + nt / 2 : nt;
;         if constexpr (Epi::HAS_MID) { if (th == 1) { PG8_SCHED; E.mid(acc, cur, wr, wc, fr, fq); PG8_SCHED; } }
;         for (int t = tlo; t < thi; t += 2) {
;             const bool last = (t == nt - 2);
;             const char* a1 = cA + (size_t)(t + 1) * kstep;
;             const char* a2 = last ? nA : cA + (size_t)(t + 2) * kstep; const char* b2 = last ? nB : cB + (size_t)(t + 2) * kstep;
;             const char* a3 = a2 + kstep; const char* b3 = b2 + kstep;
;             if (last && has_next) S.a_ready(nxt);
;             if constexpr (SP2) {
;             PG8_LDB(B0, 0, 0); PG8_LDB(B1, 0, 1); PG8_SCHED; PG8_LDA(At, 0, 0); PG8_STAGE(PG8_SA(1, 1), a1 + hstep, voffA);
;             PG8_WAIT_V(8); PG8_WAIT_L(0); PG8_BAR; PG8_MMA(0, 0, At, B0); PG8_MMA(0, 1, At, B1); PG8_BAR; PG8_SCHED;
;             PG8_LDA(At, 0, 1); PG8_STAGE(PG8_SB(0, 0), b2, voffB); PG8_STAGE(PG8_SB(0, 1), b2 + hstep, voffB); PG8_STAGE(PG8_SA(0, 0), a2, voffA);
;             PG8_WAIT_V(8); PG8_WAIT_L(0); PG8_BAR; PG8_MMA(1, 0, At, B0); PG8_MMA(1, 1, At, B1); PG8_BAR; PG8_SCHED;
.LBB0_213:
	s_add_u32 s22, s10, 0xfffc0080
	s_addc_u32 s23, s11, -1
	s_add_i32 s76, 0, 0x10000
	s_cmp_eq_u32 s49, 12
	s_cselect_b32 s81, s5, s23
	s_cselect_b32 s80, s7, s22
	s_cselect_b32 s23, s14, s37
	s_cselect_b32 s22, s16, s33
	s_add_i32 s82, 0, 0x14000
	v_add_u32_e32 v144, s76, v199
	v_add_u32_e32 v160, s82, v199
	ds_read_b128 v[132:135], v144
	ds_read_b128 v[136:139], v144 offset:1024
	ds_read_b128 v[140:143], v144 offset:2048
	ds_read_b128 v[144:147], v144 offset:3072
	ds_read_b128 v[148:151], v160
	ds_read_b128 v[152:155], v160 offset:1024
	ds_read_b128 v[156:159], v160 offset:2048
	ds_read_b128 v[160:163], v160 offset:3072
	v_lshl_add_u64 v[246:247], s[10:11], 0, v[180:181]
	s_add_i32 m0, s93, 0xc000
	ds_read_b128 v[164:167], v216
	ds_read_b128 v[168:171], v216 offset:1024
	ds_read_b128 v[188:191], v216 offset:2048
	ds_read_b128 v[218:221], v216 offset:3072
	ds_read_b128 v[230:233], v216 offset:4096
	ds_read_b128 v[234:237], v216 offset:5120
	ds_read_b128 v[238:241], v216 offset:6144
	ds_read_b128 v[242:245], v216 offset:7168
	global_load_lds_dwordx4 v[246:247], off
	v_lshl_add_u64 v[246:247], s[10:11], 0, v[182:183]
	s_add_i32 m0, s93, 0xe000
	s_nop 0
	global_load_lds_dwordx4 v[246:247], off
	s_waitcnt vmcnt(8)
	s_waitcnt lgkmcnt(0)
	s_barrier
	s_setprio 1
	s_waitcnt lgkmcnt(0)
	v_mfma_f32_16x16x32_bf16 v[128:131], v[132:135], v[164:167], v[128:131]
	v_mfma_f32_16x16x32_bf16 v[124:127], v[140:143], v[164:167], v[124:127]
	v_mfma_f32_16x16x32_bf16 v[112:115], v[132:135], v[188:191], v[112:115]
	v_mfma_f32_16x16x32_bf16 v[108:111], v[140:143], v[188:191], v[108:111]
	v_mfma_f32_16x16x32_bf16 v[96:99], v[132:135], v[230:233], v[96:99]
	v_mfma_f32_16x16x32_bf16 v[92:95], v[140:143], v[230:233], v[92:95]
	v_mfma_f32_16x16x32_bf16 v[80:83], v[132:135], v[238:241], v[80:83]
	v_mfma_f32_16x16x32_bf16 v[76:79], v[140:143], v[238:241], v[76:79]
	v_mfma_f32_16x16x32_bf16 v[128:131], v[136:139], v[168:171], v[128:131]
	v_mfma_f32_16x16x32_bf16 v[124:127], v[144:147], v[168:171], v[124:127]
	v_mfma_f32_16x16x32_bf16 v[112:115], v[136:139], v[218:221], v[112:115]
	v_mfma_f32_16x16x32_bf16 v[108:111], v[144:147], v[218:221], v[108:111]
	v_mfma_f32_16x16x32_bf16 v[96:99], v[136:139], v[234:237], v[96:99]
	v_mfma_f32_16x16x32_bf16 v[92:95], v[144:147], v[234:237], v[92:95]
	v_mfma_f32_16x16x32_bf16 v[80:83], v[136:139], v[242:245], v[80:83]
	v_mfma_f32_16x16x32_bf16 v[76:79], v[144:147], v[242:245], v[76:79]
	s_setprio 0
	s_setprio 1
	v_mfma_f32_16x16x32_bf16 v[120:123], v[148:151], v[164:167], v[120:123]
	v_mfma_f32_16x16x32_bf16 v[116:119], v[156:159], v[164:167], v[116:119]
	v_mfma_f32_16x16x32_bf16 v[104:107], v[148:151], v[188:191], v[104:107]
	v_mfma_f32_16x16x32_bf16 v[100:103], v[156:159], v[188:191], v[100:103]
	v_mfma_f32_16x16x32_bf16 v[88:91], v[148:151], v[230:233], v[88:91]
	v_mfma_f32_16x16x32_bf16 v[84:87], v[156:159], v[230:233], v[84:87]
	v_mfma_f32_16x16x32_bf16 v[72:75], v[148:151], v[238:241], v[72:75]
	v_mfma_f32_16x16x32_bf16 v[68:71], v[156:159], v[238:241], v[68:71]
	v_mfma_f32_16x16x32_bf16 v[120:123], v[152:155], v[168:171], v[120:123]
	v_mfma_f32_16x16x32_bf16 v[116:119], v[160:163], v[168:171], v[116:119]
	v_mfma_f32_16x16x32_bf16 v[104:107], v[152:155], v[218:221], v[104:107]
	v_mfma_f32_16x16x32_bf16 v[100:103], v[160:163], v[218:221], v[100:103]
	v_mfma_f32_16x16x32_bf16 v[88:91], v[152:155], v[234:237], v[88:91]
	v_mfma_f32_16x16x32_bf16 v[84:87], v[160:163], v[234:237], v[84:87]
	s_setprio 2
	s_barrier
	v_mfma_f32_16x16x32_bf16 v[72:75], v[152:155], v[242:245], v[72:75]
	v_mfma_f32_16x16x32_bf16 v[68:71], v[160:163], v[242:245], v[68:71]
	s_setprio 0
	s_add_i32 s76, s76, s21
	v_lshl_add_u64 v[246:247], s[22:23], 0, v[174:175]
	s_mov_b32 m0, s76
	ds_read_b128 v[164:167], v216 offset:16384
	ds_read_b128 v[168:171], v216 offset:17408
	ds_read_b128 v[188:191], v216 offset:18432
	ds_read_b128 v[218:221], v216 offset:19456
	ds_read_b128 v[230:233], v216 offset:20480
	ds_read_b128 v[234:237], v216 offset:21504
	ds_read_b128 v[238:241], v216 offset:22528
	ds_read_b128 v[242:245], v216 offset:23552
	global_load_lds_dwordx4 v[246:247], off
	s_add_i32 m0, s76, 0x2000
	s_add_u32 s76, s22, 0x40000
	v_lshl_add_u64 v[248:249], s[22:23], 0, v[172:173]
	s_addc_u32 s77, s23, 0
	s_add_i32 s82, s82, s21
	global_load_lds_dwordx4 v[248:249], off
	v_lshl_add_u64 v[250:251], s[76:77], 0, v[174:175]
	s_mov_b32 m0, s82
	v_lshl_add_u64 v[228:229], s[80:81], 0, v[172:173]
	global_load_lds_dwordx4 v[250:251], off
	v_lshl_add_u64 v[250:251], s[76:77], 0, v[172:173]
	s_add_i32 m0, s82, 0x2000
	s_nop 0
	global_load_lds_dwordx4 v[250:251], off
	v_lshl_add_u64 v[250:251], s[80:81], 0, v[174:175]
	s_mov_b32 m0, s93
	s_nop 0
	global_load_lds_dwordx4 v[250:251], off
	s_mov_b32 m0, s94
	s_nop 0
	global_load_lds_dwordx4 v[228:229], off
	s_waitcnt vmcnt(8)
	s_waitcnt lgkmcnt(0)
	s_barrier
; #define PG8_STAGE(bufoff, gbase, voff) do { _Pragma("unroll") for (int _i = 0; _i < 2; ++_i) \
;         __builtin_amdgcn_global_load_lds((const unsigned*)((const char*)(gbase) + (voff)[_i]), (PG8_LAS unsigned*)(lds + (bufoff) + ldsw + _i * 8192), 16, 0, 0); } while (0)
; #define PG8_LDA(dst, b, h) do { _Pragma("unroll") for (int m = 0; m < 4; ++m) _Pragma("unroll") for (int k = 0; k < 2; ++k) dst[m][k] = *(const PG8_LAS bf16x8*)(lds + PG8_SA(b, h) + aoff + m * 2048 + k * 1024); } while (0)
; #define PG8_LDB(dst, b, h) do { _Pragma("unroll") for (int n = 0; n < 2; ++n) _Pragma("unroll") for (int k = 0; k < 2; ++k) dst[n][k] = *(const PG8_LAS bf16x8*)(lds + PG8_SB(b, h) + boff + n * 2048 + k * 1024); } while (0)
; #define PG8_MMA(ai, bj, At, Bt) do { __builtin_amdgcn_s_setprio(1); _Pragma("unroll") for (int m = 0; m < 4; ++m) _Pragma("unroll") for (int n = 0; n < 2; ++n) _Pragma("unroll") for (int k = 0; k < 2; ++k) \
;         acc[ai][bj][m][n] = __builtin_amdgcn_mfma_f32_16x16x32_bf16(Bt[n][k], At[m][k], acc[ai][bj][m][n], 0, 0, 0); __builtin_amdgcn_s_setprio(0); } while (0)
; #define PG8_WAIT_V(n) asm volatile("s_waitcnt vmcnt(" #n ")" ::: "memory")
; #define PG8_WAIT_L(n) asm volatile("s_waitcnt lgkmcnt(" #n ")" ::: "memory")
; #define PG8_BAR __builtin_amdgcn_s_barrier()
; #define PG8_SCHED __builtin_amdgcn_sched_barrier(0)
; template <class Epi, class Sched, bool ALIGN_EPI = false, bool SP2 = false>
; __device__ __forceinline__ void gemm_phase(PG8_LAS unsigned char* lds, const Gemm g, const Sched& S, const Epi& E) {
;     ...
;             PG8_WAIT_V(8); PG8_WAIT_L(0); PG8_BAR; PG8_MMA(1, 0, At, B0); PG8_MMA(1, 1, At, B1); PG8_BAR; PG8_SCHED;
;             PG8_LDB(B0, 1, 0); PG8_LDB(B1, 1, 1); PG8_SCHED; PG8_LDA(At, 1, 0); PG8_STAGE(PG8_SA(0, 1), a2 + hstep, voffA);
;             PG8_WAIT_V(8); PG8_WAIT_L(0); PG8_BAR; PG8_MMA(0, 0, At, B0); PG8_MMA(0, 1, At, B1); PG8_BAR; PG8_SCHED;
	s_setprio 1
	s_waitcnt lgkmcnt(0)
	v_mfma_f32_16x16x32_bf16 v[64:67], v[132:135], v[164:167], v[64:67]
	v_mfma_f32_16x16x32_bf16 v[60:63], v[140:143], v[164:167], v[60:63]
	v_mfma_f32_16x16x32_bf16 v[48:51], v[132:135], v[188:191], v[48:51]
	v_mfma_f32_16x16x32_bf16 v[44:47], v[140:143], v[188:191], v[44:47]
	v_mfma_f32_16x16x32_bf16 v[32:35], v[132:135], v[230:233], v[32:35]
	v_mfma_f32_16x16x32_bf16 v[28:31], v[140:143], v[230:233], v[28:31]
	v_mfma_f32_16x16x32_bf16 v[16:19], v[132:135], v[238:241], v[16:19]
	v_mfma_f32_16x16x32_bf16 v[12:15], v[140:143], v[238:241], v[12:15]
	v_mfma_f32_16x16x32_bf16 v[64:67], v[136:139], v[168:171], v[64:67]
	v_mfma_f32_16x16x32_bf16 v[60:63], v[144:147], v[168:171], v[60:63]
	v_mfma_f32_16x16x32_bf16 v[48:51], v[136:139], v[218:221], v[48:51]
	v_mfma_f32_16x16x32_bf16 v[44:47], v[144:147], v[218:221], v[44:47]
	v_mfma_f32_16x16x32_bf16 v[32:35], v[136:139], v[234:237], v[32:35]
	v_mfma_f32_16x16x32_bf16 v[28:31], v[144:147], v[234:237], v[28:31]
	v_mfma_f32_16x16x32_bf16 v[16:19], v[136:139], v[242:245], v[16:19]
	v_mfma_f32_16x16x32_bf16 v[12:15], v[144:147], v[242:245], v[12:15]
	s_setprio 0
	s_setprio 1
	v_mfma_f32_16x16x32_bf16 v[56:59], v[148:151], v[164:167], v[56:59]
	v_mfma_f32_16x16x32_bf16 v[52:55], v[156:159], v[164:167], v[52:55]
	v_mfma_f32_16x16x32_bf16 v[40:43], v[148:151], v[188:191], v[40:43]
	v_mfma_f32_16x16x32_bf16 v[36:39], v[156:159], v[188:191], v[36:39]
	v_mfma_f32_16x16x32_bf16 v[24:27], v[148:151], v[230:233], v[24:27]
	v_mfma_f32_16x16x32_bf16 v[20:23], v[156:159], v[230:233], v[20:23]
	v_mfma_f32_16x16x32_bf16 v[8:11], v[148:151], v[238:241], v[8:11]
	v_mfma_f32_16x16x32_bf16 v[4:7], v[156:159], v[238:241], v[4:7]
	v_mfma_f32_16x16x32_bf16 v[56:59], v[152:155], v[168:171], v[56:59]
	v_mfma_f32_16x16x32_bf16 v[52:55], v[160:163], v[168:171], v[52:55]
	v_mfma_f32_16x16x32_bf16 v[40:43], v[152:155], v[218:221], v[40:43]
	v_mfma_f32_16x16x32_bf16 v[36:39], v[160:163], v[218:221], v[36:39]
	v_mfma_f32_16x16x32_bf16 v[24:27], v[152:155], v[234:237], v[24:27]
	v_mfma_f32_16x16x32_bf16 v[20:23], v[160:163], v[234:237], v[20:23]
	s_setprio 2
	s_barrier
	v_mfma_f32_16x16x32_bf16 v[8:11], v[152:155], v[242:245], v[8:11]
	v_mfma_f32_16x16x32_bf16 v[4:7], v[160:163], v[242:245], v[4:7]
	s_setprio 0
	s_add_i32 s82, 0, 0x18000
	s_add_i32 s83, 0, 0x1c000
	v_add_u32_e32 v144, s82, v199
	v_add_u32_e32 v160, s83, v199
	ds_read_b128 v[132:135], v144
	ds_read_b128 v[136:139], v144 offset:1024
	ds_read_b128 v[140:143], v144 offset:2048
	ds_read_b128 v[144:147], v144 offset:3072
	ds_read_b128 v[148:151], v160
	ds_read_b128 v[152:155], v160 offset:1024
	ds_read_b128 v[156:159], v160 offset:2048
	ds_read_b128 v[160:163], v160 offset:3072
	s_add_u32 s76, s80, 0x40000
	s_addc_u32 s77, s81, 0
	s_mov_b32 m0, s95
	v_lshl_add_u64 v[192:193], s[76:77], 0, v[174:175]
	ds_read_b128 v[164:167], v216 offset:32768
	ds_read_b128 v[168:171], v216 offset:33792
	ds_read_b128 v[188:191], v216 offset:34816
	ds_read_b128 v[218:221], v216 offset:35840
	ds_read_b128 v[230:233], v216 offset:36864
	ds_read_b128 v[234:237], v216 offset:37888
	ds_read_b128 v[238:241], v216 offset:38912
	ds_read_b128 v[242:245], v216 offset:39936
	global_load_lds_dwordx4 v[192:193], off
	v_lshl_add_u64 v[192:193], s[76:77], 0, v[172:173]
	s_mov_b32 m0, s92
	s_nop 0
	global_load_lds_dwordx4 v[192:193], off
	s_waitcnt vmcnt(8)
	s_waitcnt lgkmcnt(0)
	s_barrier
	s_setprio 1
	s_waitcnt lgkmcnt(0)
	v_mfma_f32_16x16x32_bf16 v[128:131], v[132:135], v[164:167], v[128:131]
	v_mfma_f32_16x16x32_bf16 v[124:127], v[140:143], v[164:167], v[124:127]
	v_mfma_f32_16x16x32_bf16 v[112:115], v[132:135], v[188:191], v[112:115]
	v_mfma_f32_16x16x32_bf16 v[108:111], v[140:143], v[188:191], v[108:111]
	v_mfma_f32_16x16x32_bf16 v[96:99], v[132:135], v[230:233], v[96:99]
	v_mfma_f32_16x16x32_bf16 v[92:95], v[140:143], v[230:233], v[92:95]
	v_mfma_f32_16x16x32_bf16 v[80:83], v[132:135], v[238:241], v[80:83]
	v_mfma_f32_16x16x32_bf16 v[76:79], v[140:143], v[238:241], v[76:79]
	v_mfma_f32_16x16x32_bf16 v[128:131], v[136:139], v[168:171], v[128:131]
	v_mfma_f32_16x16x32_bf16 v[124:127], v[144:147], v[168:171], v[124:127]
	v_mfma_f32_16x16x32_bf16 v[112:115], v[136:139], v[218:221], v[112:115]
	v_mfma_f32_16x16x32_bf16 v[108:111], v[144:147], v[218:221], v[108:111]
	v_mfma_f32_16x16x32_bf16 v[96:99], v[136:139], v[234:237], v[96:99]
	v_mfma_f32_16x16x32_bf16 v[92:95], v[144:147], v[234:237], v[92:95]
	v_mfma_f32_16x16x32_bf16 v[80:83], v[136:139], v[242:245], v[80:83]
	v_mfma_f32_16x16x32_bf16 v[76:79], v[144:147], v[242:245], v[76:79]
	s_setprio 0
	s_setprio 1
	v_mfma_f32_16x16x32_bf16 v[120:123], v[148:151], v[164:167], v[120:123]
	v_mfma_f32_16x16x32_bf16 v[116:119], v[156:159], v[164:167], v[116:119]
	v_mfma_f32_16x16x32_bf16 v[104:107], v[148:151], v[188:191], v[104:107]
	v_mfma_f32_16x16x32_bf16 v[100:103], v[156:159], v[188:191], v[100:103]
	v_mfma_f32_16x16x32_bf16 v[88:91], v[148:151], v[230:233], v[88:91]
	v_mfma_f32_16x16x32_bf16 v[84:87], v[156:159], v[230:233], v[84:87]
	v_mfma_f32_16x16x32_bf16 v[72:75], v[148:151], v[238:241], v[72:75]
	v_mfma_f32_16x16x32_bf16 v[68:71], v[156:159], v[238:241], v[68:71]
	v_mfma_f32_16x16x32_bf16 v[120:123], v[152:155], v[168:171], v[120:123]
	v_mfma_f32_16x16x32_bf16 v[116:119], v[160:163], v[168:171], v[116:119]
	v_mfma_f32_16x16x32_bf16 v[104:107], v[152:155], v[218:221], v[104:107]
	v_mfma_f32_16x16x32_bf16 v[100:103], v[160:163], v[218:221], v[100:103]
	v_mfma_f32_16x16x32_bf16 v[88:91], v[152:155], v[234:237], v[88:91]
	v_mfma_f32_16x16x32_bf16 v[84:87], v[160:163], v[234:237], v[84:87]
	s_setprio 2
	s_barrier
; #define PG8_STAGE(bufoff, gbase, voff) do { _Pragma("unroll") for (int _i = 0; _i < 2; ++_i) \
;         __builtin_amdgcn_global_load_lds((const unsigned*)((const char*)(gbase) + (voff)[_i]), (PG8_LAS unsigned*)(lds + (bufoff) + ldsw + _i * 8192), 16, 0, 0); } while (0)
; #define PG8_LDA(dst, b, h) do { _Pragma("unroll") for (int m = 0; m < 4; ++m) _Pragma("unroll") for (int k = 0; k < 2; ++k) dst[m][k] = *(const PG8_LAS bf16x8*)(lds + PG8_SA(b, h) + aoff + m * 2048 + k * 1024); } while (0)
; #define PG8_MMA(ai, bj, At, Bt) do { __builtin_amdgcn_s_setprio(1); _Pragma("unroll") for (int m = 0; m < 4; ++m) _Pragma("unroll") for (int n = 0; n < 2; ++n) _Pragma("unroll") for (int k = 0; k < 2; ++k) \
;         acc[ai][bj][m][n] = __builtin_amdgcn_mfma_f32_16x16x32_bf16(Bt[n][k], At[m][k], acc[ai][bj][m][n], 0, 0, 0); __builtin_amdgcn_s_setprio(0); } while (0)
; #define PG8_WAIT_V(n) asm volatile("s_waitcnt vmcnt(" #n ")" ::: "memory")
; #define PG8_WAIT_L(n) asm volatile("s_waitcnt lgkmcnt(" #n ")" ::: "memory")
; #define PG8_BAR __builtin_amdgcn_s_barrier()
; #define PG8_SCHED __builtin_amdgcn_sched_barrier(0)
; template <class Epi, class Sched, bool ALIGN_EPI = false, bool SP2 = false>
; __device__ __forceinline__ void gemm_phase(PG8_LAS unsigned char* lds, const Gemm g, const Sched& S, const Epi& E) {
;     ...
;             PG8_LDA(At, 1, 1); PG8_STAGE(PG8_SB(1, 0), b3, voffB); PG8_STAGE(PG8_SB(1, 1), b3 + hstep, voffB); PG8_STAGE(PG8_SA(1, 0), a3, voffA);
;             PG8_WAIT_V(8); PG8_WAIT_L(0); PG8_BAR; PG8_MMA(1, 0, At, B0); PG8_MMA(1, 1, At, B1); PG8_BAR; PG8_SCHED;
;     ...
;         if constexpr (ALIGN_EPI) { if (wr == 0) PG8_BAR; }
	v_mfma_f32_16x16x32_bf16 v[72:75], v[152:155], v[242:245], v[72:75]
	v_mfma_f32_16x16x32_bf16 v[68:71], v[160:163], v[242:245], v[68:71]
	s_setprio 0
	s_add_i32 s76, s82, s21
	v_lshl_add_u64 v[192:193], v[246:247], 0, s[50:51]
	s_mov_b32 m0, s76
	ds_read_b128 v[164:167], v216 offset:49152
	ds_read_b128 v[168:171], v216 offset:50176
	ds_read_b128 v[188:191], v216 offset:51200
	ds_read_b128 v[218:221], v216 offset:52224
	ds_read_b128 v[230:233], v216 offset:53248
	ds_read_b128 v[234:237], v216 offset:54272
	ds_read_b128 v[238:241], v216 offset:55296
	ds_read_b128 v[242:245], v216 offset:56320
	global_load_lds_dwordx4 v[192:193], off
	s_add_i32 m0, s76, 0x2000
	s_add_u32 s22, s22, 0x40080
	v_lshl_add_u64 v[192:193], v[248:249], 0, s[50:51]
	s_addc_u32 s23, s23, 0
	s_add_i32 s76, s83, s21
	global_load_lds_dwordx4 v[192:193], off
	v_lshl_add_u64 v[192:193], s[22:23], 0, v[174:175]
	s_mov_b32 m0, s76
	s_nop 0
	global_load_lds_dwordx4 v[192:193], off
	v_lshl_add_u64 v[192:193], s[22:23], 0, v[172:173]
	s_add_i32 m0, s76, 0x2000
	s_nop 0
	global_load_lds_dwordx4 v[192:193], off
	v_lshl_add_u64 v[192:193], v[250:251], 0, s[50:51]
	s_mov_b32 m0, s46
	s_nop 0
	global_load_lds_dwordx4 v[192:193], off
	v_lshl_add_u64 v[192:193], v[228:229], 0, s[50:51]
	s_mov_b32 m0, s47
	s_nop 0
	global_load_lds_dwordx4 v[192:193], off
	s_waitcnt vmcnt(8)
	s_waitcnt lgkmcnt(0)
	s_barrier
	s_setprio 1
	s_waitcnt lgkmcnt(0)
	v_mfma_f32_16x16x32_bf16 v[64:67], v[132:135], v[164:167], v[64:67]
	v_mfma_f32_16x16x32_bf16 v[60:63], v[140:143], v[164:167], v[60:63]
	v_mfma_f32_16x16x32_bf16 v[48:51], v[132:135], v[188:191], v[48:51]
	v_mfma_f32_16x16x32_bf16 v[44:47], v[140:143], v[188:191], v[44:47]
	v_mfma_f32_16x16x32_bf16 v[32:35], v[132:135], v[230:233], v[32:35]
	v_mfma_f32_16x16x32_bf16 v[28:31], v[140:143], v[230:233], v[28:31]
	v_mfma_f32_16x16x32_bf16 v[16:19], v[132:135], v[238:241], v[16:19]
	v_mfma_f32_16x16x32_bf16 v[12:15], v[140:143], v[238:241], v[12:15]
	v_mfma_f32_16x16x32_bf16 v[64:67], v[136:139], v[168:171], v[64:67]
	v_mfma_f32_16x16x32_bf16 v[60:63], v[144:147], v[168:171], v[60:63]
	v_mfma_f32_16x16x32_bf16 v[48:51], v[136:139], v[218:221], v[48:51]
	v_mfma_f32_16x16x32_bf16 v[44:47], v[144:147], v[218:221], v[44:47]
	v_mfma_f32_16x16x32_bf16 v[32:35], v[136:139], v[234:237], v[32:35]
	v_mfma_f32_16x16x32_bf16 v[28:31], v[144:147], v[234:237], v[28:31]
	v_mfma_f32_16x16x32_bf16 v[16:19], v[136:139], v[242:245], v[16:19]
	v_mfma_f32_16x16x32_bf16 v[12:15], v[144:147], v[242:245], v[12:15]
	s_setprio 0
	s_setprio 1
	v_mfma_f32_16x16x32_bf16 v[56:59], v[148:151], v[164:167], v[56:59]
	v_mfma_f32_16x16x32_bf16 v[52:55], v[156:159], v[164:167], v[52:55]
	v_mfma_f32_16x16x32_bf16 v[40:43], v[148:151], v[188:191], v[40:43]
	v_mfma_f32_16x16x32_bf16 v[36:39], v[156:159], v[188:191], v[36:39]
	v_mfma_f32_16x16x32_bf16 v[24:27], v[148:151], v[230:233], v[24:27]
	v_mfma_f32_16x16x32_bf16 v[20:23], v[156:159], v[230:233], v[20:23]
	v_mfma_f32_16x16x32_bf16 v[8:11], v[148:151], v[238:241], v[8:11]
	v_mfma_f32_16x16x32_bf16 v[4:7], v[156:159], v[238:241], v[4:7]
	v_mfma_f32_16x16x32_bf16 v[56:59], v[152:155], v[168:171], v[56:59]
	v_mfma_f32_16x16x32_bf16 v[52:55], v[160:163], v[168:171], v[52:55]
	v_mfma_f32_16x16x32_bf16 v[40:43], v[152:155], v[218:221], v[40:43]
	v_mfma_f32_16x16x32_bf16 v[36:39], v[160:163], v[218:221], v[36:39]
	v_mfma_f32_16x16x32_bf16 v[24:27], v[152:155], v[234:237], v[24:27]
	v_mfma_f32_16x16x32_bf16 v[20:23], v[160:163], v[234:237], v[20:23]
	s_setprio 2
	s_barrier
	v_mfma_f32_16x16x32_bf16 v[8:11], v[152:155], v[242:245], v[8:11]
	v_mfma_f32_16x16x32_bf16 v[4:7], v[160:163], v[242:245], v[4:7]
	s_setprio 0
	s_add_i32 s49, s49, 2
	s_add_u32 s10, s10, 0x100
	s_addc_u32 s11, s11, 0
	s_add_u32 s33, s33, 0x100
	s_addc_u32 s37, s37, 0
	s_cmp_gt_u32 s49, 13
	s_cbranch_scc0 .LBB0_213
	s_and_b64 vcc, exec, s[54:55]
	s_cbranch_vccz .LBB0_216
	s_barrier

; #define PG8_STAGE(bufoff, gbase, voff) do { _Pragma("unroll") for (int _i = 0; _i < 2; ++_i) \
;         __builtin_amdgcn_global_load_lds((const unsigned*)((const char*)(gbase) + (voff)[_i]), (PG8_LAS unsigned*)(lds + (bufoff) + ldsw + _i * 8192), 16, 0, 0); } while (0)
; #define PG8_LDA(dst, b, h) do { _Pragma("unroll") for (int m = 0; m < 4; ++m) _Pragma("unroll") for (int k = 0; k < 2; ++k) dst[m][k] = *(const PG8_LAS bf16x8*)(lds + PG8_SA(b, h) + aoff + m * 2048 + k * 1024); } while (0)
; #define PG8_LDB(dst, b, h) do { _Pragma("unroll") for (int n = 0; n < 2; ++n) _Pragma("unroll") for (int k = 0; k < 2; ++k) dst[n][k] = *(const PG8_LAS bf16x8*)(lds + PG8_SB(b, h) + boff + n * 2048 + k * 1024); } while (0)
; #define PG8_WAIT_V(n) asm volatile("s_waitcnt vmcnt(" #n ")" ::: "memory")
; #define PG8_WAIT_L(n) asm volatile("s_waitcnt lgkmcnt(" #n ")" ::: "memory")
; #define PG8_BAR __builtin_amdgcn_s_barrier()
; template <class Epi, class Sched, bool ALIGN_EPI = false, bool SP2 = false>
; __device__ __forceinline__ void gemm_phase(PG8_LAS unsigned char* lds, const Gemm g, const Sched& S, const Epi& E) {
;     ...
;         for (int th = 0; th < (Epi::HAS_MID ? 2 : 1); ++th) { const int tlo = Epi::HAS_MID ? th * (nt / 2) : 0, thi = Epi::HAS_MID ? tlo + nt / 2 : nt;
;         if constexpr (Epi::HAS_MID) { if (th == 1) { PG8_SCHED; E.mid(acc, cur, wr, wc, fr, fq); PG8_SCHED; } }
;         for (int t = tlo; t < thi; t += 2) {
;             const bool last = (t == nt - 2);
;             const char* a1 = cA + (size_t)(t + 1) * kstep;
;             const char* a2 = last ? nA : cA + (size_t)(t + 2) * kstep; const char* b2 = last ? nB : cB + (size_t)(t + 2) * kstep;
;             const char* a3 = a2 + kstep; const char* b3 = b2 + kstep;
;             if (last && has_next) S.a_ready(nxt);
;             if constexpr (SP2) {
;             PG8_LDB(B0, 0, 0); PG8_LDB(B1, 0, 1); PG8_SCHED; PG8_LDA(At, 0, 0); PG8_STAGE(PG8_SA(1, 1), a1 + hstep, voffA);
;             PG8_WAIT_V(8); PG8_WAIT_L(0); PG8_BAR; PG8_MMA(0, 0, At, B0); PG8_MMA(0, 1, At, B1); PG8_BAR; PG8_SCHED;
;             PG8_LDA(At, 0, 1); PG8_STAGE(PG8_SB(0, 0), b2, voffB); PG8_STAGE(PG8_SB(0, 1), b2 + hstep, voffB); PG8_STAGE(PG8_SA(0, 0), a2, voffA);
;             PG8_WAIT_V(8); PG8_WAIT_L(0); PG8_BAR; PG8_MMA(1, 0, At, B0); PG8_MMA(1, 1, At, B1); PG8_BAR; PG8_SCHED;
.LBB0_603:
	s_add_i32 s16, s16, 2
	s_add_u32 s82, s80, s44
	s_addc_u32 s83, s81, s45
	s_add_u32 s94, s54, s44
	s_addc_u32 s95, s55, s45
	s_add_i32 s78, 0, 0x10000
	s_cmp_eq_u32 s44, s48
	s_cselect_b32 vcc_hi, s77, s83
	s_cselect_b32 vcc_lo, s37, s82
	v_add_u32_e32 v2, s78, v231
	s_cselect_b32 s95, s87, s95
	s_cselect_b32 s94, s96, s94
	s_add_i32 s79, 0, 0x14000
	ds_read_b128 v[136:139], v2
	ds_read_b128 v[140:143], v2 offset:1024
	ds_read_b128 v[144:147], v2 offset:2048
	ds_read_b128 v[148:151], v2 offset:3072
	v_add_u32_e32 v2, s79, v231
	ds_read_b128 v[152:155], v2
	ds_read_b128 v[156:159], v2 offset:1024
	ds_read_b128 v[160:163], v2 offset:2048
	ds_read_b128 v[170:173], v2 offset:3072
	v_lshl_add_u64 v[164:165], v[134:135], 0, s[44:45]
	s_add_i32 m0, s28, 0xc000
	ds_read_b128 v[174:177], v233
	ds_read_b128 v[178:181], v233 offset:1024
	ds_read_b128 v[182:185], v233 offset:2048
	ds_read_b128 v[186:189], v233 offset:3072
	ds_read_b128 v[206:209], v233 offset:4096
	ds_read_b128 v[210:213], v233 offset:5120
	ds_read_b128 v[214:217], v233 offset:6144
	ds_read_b128 v[218:221], v233 offset:7168
	global_load_lds_dwordx4 v[164:165], off
	v_lshl_add_u64 v[164:165], v[4:5], 0, s[44:45]
	s_add_i32 m0, s28, 0xe000
	s_nop 0
	global_load_lds_dwordx4 v[164:165], off
	s_waitcnt vmcnt(8)
	s_waitcnt lgkmcnt(0)
	s_barrier
	s_setprio 1
	s_waitcnt lgkmcnt(0)
	v_mfma_f32_16x16x32_bf16 v[130:133], v[136:139], v[174:177], v[130:133]
	v_mfma_f32_16x16x32_bf16 v[126:129], v[144:147], v[174:177], v[126:129]
	v_mfma_f32_16x16x32_bf16 v[114:117], v[136:139], v[182:185], v[114:117]
	v_mfma_f32_16x16x32_bf16 v[110:113], v[144:147], v[182:185], v[110:113]
	v_mfma_f32_16x16x32_bf16 v[98:101], v[136:139], v[206:209], v[98:101]
	v_mfma_f32_16x16x32_bf16 v[94:97], v[144:147], v[206:209], v[94:97]
	v_mfma_f32_16x16x32_bf16 v[82:85], v[136:139], v[214:217], v[82:85]
	v_mfma_f32_16x16x32_bf16 v[78:81], v[144:147], v[214:217], v[78:81]
	v_mfma_f32_16x16x32_bf16 v[130:133], v[140:143], v[178:181], v[130:133]
	v_mfma_f32_16x16x32_bf16 v[126:129], v[148:151], v[178:181], v[126:129]
	v_mfma_f32_16x16x32_bf16 v[114:117], v[140:143], v[186:189], v[114:117]
	v_mfma_f32_16x16x32_bf16 v[110:113], v[148:151], v[186:189], v[110:113]
	v_mfma_f32_16x16x32_bf16 v[98:101], v[140:143], v[210:213], v[98:101]
	v_mfma_f32_16x16x32_bf16 v[94:97], v[148:151], v[210:213], v[94:97]
	v_mfma_f32_16x16x32_bf16 v[82:85], v[140:143], v[218:221], v[82:85]
	v_mfma_f32_16x16x32_bf16 v[78:81], v[148:151], v[218:221], v[78:81]
	s_setprio 0
	s_setprio 1
	v_mfma_f32_16x16x32_bf16 v[122:125], v[152:155], v[174:177], v[122:125]
	v_mfma_f32_16x16x32_bf16 v[118:121], v[160:163], v[174:177], v[118:121]
	v_mfma_f32_16x16x32_bf16 v[106:109], v[152:155], v[182:185], v[106:109]
	v_mfma_f32_16x16x32_bf16 v[102:105], v[160:163], v[182:185], v[102:105]
	v_mfma_f32_16x16x32_bf16 v[90:93], v[152:155], v[206:209], v[90:93]
	v_mfma_f32_16x16x32_bf16 v[86:89], v[160:163], v[206:209], v[86:89]
	v_mfma_f32_16x16x32_bf16 v[74:77], v[152:155], v[214:217], v[74:77]
	v_mfma_f32_16x16x32_bf16 v[70:73], v[160:163], v[214:217], v[70:73]
	v_mfma_f32_16x16x32_bf16 v[122:125], v[156:159], v[178:181], v[122:125]
	v_mfma_f32_16x16x32_bf16 v[118:121], v[170:173], v[178:181], v[118:121]
	v_mfma_f32_16x16x32_bf16 v[106:109], v[156:159], v[186:189], v[106:109]
	v_mfma_f32_16x16x32_bf16 v[102:105], v[170:173], v[186:189], v[102:105]
	v_mfma_f32_16x16x32_bf16 v[90:93], v[156:159], v[210:213], v[90:93]
	v_mfma_f32_16x16x32_bf16 v[86:89], v[170:173], v[210:213], v[86:89]
	s_setprio 2
	s_barrier
	v_mfma_f32_16x16x32_bf16 v[74:77], v[156:159], v[218:221], v[74:77]
	v_mfma_f32_16x16x32_bf16 v[70:73], v[170:173], v[218:221], v[70:73]
	s_setprio 0
	s_add_i32 s78, s78, s21
	v_lshl_add_u64 v[164:165], s[94:95], 0, v[198:199]
	s_mov_b32 m0, s78
	ds_read_b128 v[174:177], v233 offset:16384
	ds_read_b128 v[178:181], v233 offset:17408
	ds_read_b128 v[182:185], v233 offset:18432
	ds_read_b128 v[186:189], v233 offset:19456
	ds_read_b128 v[206:209], v233 offset:20480
	ds_read_b128 v[210:213], v233 offset:21504
	ds_read_b128 v[214:217], v233 offset:22528
	ds_read_b128 v[218:221], v233 offset:23552
	global_load_lds_dwordx4 v[164:165], off
	s_add_i32 m0, s78, 0x2000
	s_add_u32 s82, s94, 0x40000
	v_lshl_add_u64 v[192:193], s[94:95], 0, v[190:191]
	s_addc_u32 s83, s95, 0
	s_add_i32 s78, s79, s21
	global_load_lds_dwordx4 v[192:193], off
	v_lshl_add_u64 v[234:235], s[82:83], 0, v[198:199]
	s_mov_b32 m0, s78
	v_lshl_add_u64 v[236:237], vcc, 0, v[190:191]
	global_load_lds_dwordx4 v[234:235], off
	v_lshl_add_u64 v[234:235], s[82:83], 0, v[190:191]
	s_add_i32 m0, s78, 0x2000
	s_nop 0
	global_load_lds_dwordx4 v[234:235], off
	v_lshl_add_u64 v[234:235], vcc, 0, v[198:199]
	s_mov_b32 m0, s28
	s_nop 0
	global_load_lds_dwordx4 v[234:235], off
	s_mov_b32 m0, s29
	s_nop 0
	global_load_lds_dwordx4 v[236:237], off
	s_waitcnt vmcnt(8)
	s_waitcnt lgkmcnt(0)
	s_barrier
; #define PG8_STAGE(bufoff, gbase, voff) do { _Pragma("unroll") for (int _i = 0; _i < 2; ++_i) \
;         __builtin_amdgcn_global_load_lds((const unsigned*)((const char*)(gbase) + (voff)[_i]), (PG8_LAS unsigned*)(lds + (bufoff) + ldsw + _i * 8192), 16, 0, 0); } while (0)
; #define PG8_LDA(dst, b, h) do { _Pragma("unroll") for (int m = 0; m < 4; ++m) _Pragma("unroll") for (int k = 0; k < 2; ++k) dst[m][k] = *(const PG8_LAS bf16x8*)(lds + PG8_SA(b, h) + aoff + m * 2048 + k * 1024); } while (0)
; #define PG8_LDB(dst, b, h) do { _Pragma("unroll") for (int n = 0; n < 2; ++n) _Pragma("unroll") for (int k = 0; k < 2; ++k) dst[n][k] = *(const PG8_LAS bf16x8*)(lds + PG8_SB(b, h) + boff + n * 2048 + k * 1024); } while (0)
; #define PG8_MMA(ai, bj, At, Bt) do { __builtin_amdgcn_s_setprio(1); _Pragma("unroll") for (int m = 0; m < 4; ++m) _Pragma("unroll") for (int n = 0; n < 2; ++n) _Pragma("unroll") for (int k = 0; k < 2; ++k) \
;         acc[ai][bj][m][n] = __builtin_amdgcn_mfma_f32_16x16x32_bf16(Bt[n][k], At[m][k], acc[ai][bj][m][n], 0, 0, 0); __builtin_amdgcn_s_setprio(0); } while (0)
; #define PG8_WAIT_V(n) asm volatile("s_waitcnt vmcnt(" #n ")" ::: "memory")
; #define PG8_WAIT_L(n) asm volatile("s_waitcnt lgkmcnt(" #n ")" ::: "memory")
; #define PG8_BAR __builtin_amdgcn_s_barrier()
; #define PG8_SCHED __builtin_amdgcn_sched_barrier(0)
; template <class Epi, class Sched, bool ALIGN_EPI = false, bool SP2 = false>
; __device__ __forceinline__ void gemm_phase(PG8_LAS unsigned char* lds, const Gemm g, const Sched& S, const Epi& E) {
;     ...
;             PG8_WAIT_V(8); PG8_WAIT_L(0); PG8_BAR; PG8_MMA(1, 0, At, B0); PG8_MMA(1, 1, At, B1); PG8_BAR; PG8_SCHED;
;             PG8_LDB(B0, 1, 0); PG8_LDB(B1, 1, 1); PG8_SCHED; PG8_LDA(At, 1, 0); PG8_STAGE(PG8_SA(0, 1), a2 + hstep, voffA);
;             PG8_WAIT_V(8); PG8_WAIT_L(0); PG8_BAR; PG8_MMA(0, 0, At, B0); PG8_MMA(0, 1, At, B1); PG8_BAR; PG8_SCHED;
	s_setprio 1
	s_waitcnt lgkmcnt(0)
	v_mfma_f32_16x16x32_bf16 v[66:69], v[136:139], v[174:177], v[66:69]
	v_mfma_f32_16x16x32_bf16 v[62:65], v[144:147], v[174:177], v[62:65]
	v_mfma_f32_16x16x32_bf16 v[50:53], v[136:139], v[182:185], v[50:53]
	v_mfma_f32_16x16x32_bf16 v[46:49], v[144:147], v[182:185], v[46:49]
	v_mfma_f32_16x16x32_bf16 v[34:37], v[136:139], v[206:209], v[34:37]
	v_mfma_f32_16x16x32_bf16 v[30:33], v[144:147], v[206:209], v[30:33]
	v_mfma_f32_16x16x32_bf16 v[18:21], v[136:139], v[214:217], v[18:21]
	v_mfma_f32_16x16x32_bf16 v[14:17], v[144:147], v[214:217], v[14:17]
	v_mfma_f32_16x16x32_bf16 v[66:69], v[140:143], v[178:181], v[66:69]
	v_mfma_f32_16x16x32_bf16 v[62:65], v[148:151], v[178:181], v[62:65]
	v_mfma_f32_16x16x32_bf16 v[50:53], v[140:143], v[186:189], v[50:53]
	v_mfma_f32_16x16x32_bf16 v[46:49], v[148:151], v[186:189], v[46:49]
	v_mfma_f32_16x16x32_bf16 v[34:37], v[140:143], v[210:213], v[34:37]
	v_mfma_f32_16x16x32_bf16 v[30:33], v[148:151], v[210:213], v[30:33]
	v_mfma_f32_16x16x32_bf16 v[18:21], v[140:143], v[218:221], v[18:21]
	v_mfma_f32_16x16x32_bf16 v[14:17], v[148:151], v[218:221], v[14:17]
	s_setprio 0
	s_setprio 1
	v_mfma_f32_16x16x32_bf16 v[58:61], v[152:155], v[174:177], v[58:61]
	v_mfma_f32_16x16x32_bf16 v[54:57], v[160:163], v[174:177], v[54:57]
	v_mfma_f32_16x16x32_bf16 v[42:45], v[152:155], v[182:185], v[42:45]
	v_mfma_f32_16x16x32_bf16 v[38:41], v[160:163], v[182:185], v[38:41]
	v_mfma_f32_16x16x32_bf16 v[26:29], v[152:155], v[206:209], v[26:29]
	v_mfma_f32_16x16x32_bf16 v[22:25], v[160:163], v[206:209], v[22:25]
	v_mfma_f32_16x16x32_bf16 v[10:13], v[152:155], v[214:217], v[10:13]
	v_mfma_f32_16x16x32_bf16 v[6:9], v[160:163], v[214:217], v[6:9]
	v_mfma_f32_16x16x32_bf16 v[58:61], v[156:159], v[178:181], v[58:61]
	v_mfma_f32_16x16x32_bf16 v[54:57], v[170:173], v[178:181], v[54:57]
	v_mfma_f32_16x16x32_bf16 v[42:45], v[156:159], v[186:189], v[42:45]
	v_mfma_f32_16x16x32_bf16 v[38:41], v[170:173], v[186:189], v[38:41]
	v_mfma_f32_16x16x32_bf16 v[26:29], v[156:159], v[210:213], v[26:29]
	v_mfma_f32_16x16x32_bf16 v[22:25], v[170:173], v[210:213], v[22:25]
	s_setprio 2
	s_barrier
	v_mfma_f32_16x16x32_bf16 v[10:13], v[156:159], v[218:221], v[10:13]
	v_mfma_f32_16x16x32_bf16 v[6:9], v[170:173], v[218:221], v[6:9]
	s_setprio 0
	s_add_i32 s78, 0, 0x18000
	v_add_u32_e32 v2, s78, v231
	s_add_i32 s79, 0, 0x1c000
	ds_read_b128 v[136:139], v2
	ds_read_b128 v[140:143], v2 offset:1024
	ds_read_b128 v[144:147], v2 offset:2048
	ds_read_b128 v[148:151], v2 offset:3072
	v_add_u32_e32 v2, s79, v231
	ds_read_b128 v[152:155], v2
	ds_read_b128 v[156:159], v2 offset:1024
	ds_read_b128 v[160:163], v2 offset:2048
	ds_read_b128 v[170:173], v2 offset:3072
	s_add_u32 s82, vcc_lo, 0x40000
	s_addc_u32 s83, vcc_hi, 0
	s_mov_b32 m0, s30
	v_lshl_add_u64 v[238:239], s[82:83], 0, v[198:199]
	ds_read_b128 v[174:177], v233 offset:32768
	ds_read_b128 v[178:181], v233 offset:33792
	ds_read_b128 v[182:185], v233 offset:34816
	ds_read_b128 v[186:189], v233 offset:35840
	ds_read_b128 v[206:209], v233 offset:36864
	ds_read_b128 v[210:213], v233 offset:37888
	ds_read_b128 v[214:217], v233 offset:38912
	ds_read_b128 v[218:221], v233 offset:39936
	global_load_lds_dwordx4 v[238:239], off
	v_lshl_add_u64 v[238:239], s[82:83], 0, v[190:191]
	s_mov_b32 m0, s31
	s_nop 0
	global_load_lds_dwordx4 v[238:239], off
	s_waitcnt vmcnt(8)
	s_waitcnt lgkmcnt(0)
	s_barrier
	s_setprio 1
	s_waitcnt lgkmcnt(0)
	v_mfma_f32_16x16x32_bf16 v[130:133], v[136:139], v[174:177], v[130:133]
	v_mfma_f32_16x16x32_bf16 v[126:129], v[144:147], v[174:177], v[126:129]
	v_mfma_f32_16x16x32_bf16 v[114:117], v[136:139], v[182:185], v[114:117]
	v_mfma_f32_16x16x32_bf16 v[110:113], v[144:147], v[182:185], v[110:113]
	v_mfma_f32_16x16x32_bf16 v[98:101], v[136:139], v[206:209], v[98:101]
	v_mfma_f32_16x16x32_bf16 v[94:97], v[144:147], v[206:209], v[94:97]
	v_mfma_f32_16x16x32_bf16 v[82:85], v[136:139], v[214:217], v[82:85]
	v_mfma_f32_16x16x32_bf16 v[78:81], v[144:147], v[214:217], v[78:81]
	v_mfma_f32_16x16x32_bf16 v[130:133], v[140:143], v[178:181], v[130:133]
	v_mfma_f32_16x16x32_bf16 v[126:129], v[148:151], v[178:181], v[126:129]
	v_mfma_f32_16x16x32_bf16 v[114:117], v[140:143], v[186:189], v[114:117]
	v_mfma_f32_16x16x32_bf16 v[110:113], v[148:151], v[186:189], v[110:113]
	v_mfma_f32_16x16x32_bf16 v[98:101], v[140:143], v[210:213], v[98:101]
	v_mfma_f32_16x16x32_bf16 v[94:97], v[148:151], v[210:213], v[94:97]
	v_mfma_f32_16x16x32_bf16 v[82:85], v[140:143], v[218:221], v[82:85]
	v_mfma_f32_16x16x32_bf16 v[78:81], v[148:151], v[218:221], v[78:81]
	s_setprio 0
	s_setprio 1
	v_mfma_f32_16x16x32_bf16 v[122:125], v[152:155], v[174:177], v[122:125]
	v_mfma_f32_16x16x32_bf16 v[118:121], v[160:163], v[174:177], v[118:121]
	v_mfma_f32_16x16x32_bf16 v[106:109], v[152:155], v[182:185], v[106:109]
	v_mfma_f32_16x16x32_bf16 v[102:105], v[160:163], v[182:185], v[102:105]
	v_mfma_f32_16x16x32_bf16 v[90:93], v[152:155], v[206:209], v[90:93]
	v_mfma_f32_16x16x32_bf16 v[86:89], v[160:163], v[206:209], v[86:89]
	v_mfma_f32_16x16x32_bf16 v[74:77], v[152:155], v[214:217], v[74:77]
	v_mfma_f32_16x16x32_bf16 v[70:73], v[160:163], v[214:217], v[70:73]
	v_mfma_f32_16x16x32_bf16 v[122:125], v[156:159], v[178:181], v[122:125]
	v_mfma_f32_16x16x32_bf16 v[118:121], v[170:173], v[178:181], v[118:121]
	v_mfma_f32_16x16x32_bf16 v[106:109], v[156:159], v[186:189], v[106:109]
	v_mfma_f32_16x16x32_bf16 v[102:105], v[170:173], v[186:189], v[102:105]
	v_mfma_f32_16x16x32_bf16 v[90:93], v[156:159], v[210:213], v[90:93]
	v_mfma_f32_16x16x32_bf16 v[86:89], v[170:173], v[210:213], v[86:89]
	s_setprio 2
	s_barrier
; #define PG8_STAGE(bufoff, gbase, voff) do { _Pragma("unroll") for (int _i = 0; _i < 2; ++_i) \
;         __builtin_amdgcn_global_load_lds((const unsigned*)((const char*)(gbase) + (voff)[_i]), (PG8_LAS unsigned*)(lds + (bufoff) + ldsw + _i * 8192), 16, 0, 0); } while (0)
; #define PG8_LDA(dst, b, h) do { _Pragma("unroll") for (int m = 0; m < 4; ++m) _Pragma("unroll") for (int k = 0; k < 2; ++k) dst[m][k] = *(const PG8_LAS bf16x8*)(lds + PG8_SA(b, h) + aoff + m * 2048 + k * 1024); } while (0)
; #define PG8_MMA(ai, bj, At, Bt) do { __builtin_amdgcn_s_setprio(1); _Pragma("unroll") for (int m = 0; m < 4; ++m) _Pragma("unroll") for (int n = 0; n < 2; ++n) _Pragma("unroll") for (int k = 0; k < 2; ++k) \
;         acc[ai][bj][m][n] = __builtin_amdgcn_mfma_f32_16x16x32_bf16(Bt[n][k], At[m][k], acc[ai][bj][m][n], 0, 0, 0); __builtin_amdgcn_s_setprio(0); } while (0)
; #define PG8_WAIT_V(n) asm volatile("s_waitcnt vmcnt(" #n ")" ::: "memory")
; #define PG8_WAIT_L(n) asm volatile("s_waitcnt lgkmcnt(" #n ")" ::: "memory")
; #define PG8_BAR __builtin_amdgcn_s_barrier()
; #define PG8_SCHED __builtin_amdgcn_sched_barrier(0)
; template <class Epi, class Sched, bool ALIGN_EPI = false, bool SP2 = false>
; __device__ __forceinline__ void gemm_phase(PG8_LAS unsigned char* lds, const Gemm g, const Sched& S, const Epi& E) {
;     ...
;         for (int th = 0; th < (Epi::HAS_MID ? 2 : 1); ++th) { const int tlo = Epi::HAS_MID ? th * (nt / 2) : 0, thi = Epi::HAS_MID ? tlo + nt / 2 : nt;
;         if constexpr (Epi::HAS_MID) { if (th == 1) { PG8_SCHED; E.mid(acc, cur, wr, wc, fr, fq); PG8_SCHED; } }
;     ...
;             PG8_LDA(At, 1, 1); PG8_STAGE(PG8_SB(1, 0), b3, voffB); PG8_STAGE(PG8_SB(1, 1), b3 + hstep, voffB); PG8_STAGE(PG8_SA(1, 0), a3, voffA);
;             PG8_WAIT_V(8); PG8_WAIT_L(0); PG8_BAR; PG8_MMA(1, 0, At, B0); PG8_MMA(1, 1, At, B1); PG8_BAR; PG8_SCHED;
	v_mfma_f32_16x16x32_bf16 v[74:77], v[156:159], v[218:221], v[74:77]
	v_mfma_f32_16x16x32_bf16 v[70:73], v[170:173], v[218:221], v[70:73]
	s_setprio 0
	s_add_i32 s78, s78, s21
	v_lshl_add_u64 v[164:165], v[164:165], 0, s[50:51]
	s_mov_b32 m0, s78
	ds_read_b128 v[174:177], v233 offset:49152
	ds_read_b128 v[178:181], v233 offset:50176
	ds_read_b128 v[182:185], v233 offset:51200
	ds_read_b128 v[186:189], v233 offset:52224
	ds_read_b128 v[206:209], v233 offset:53248
	ds_read_b128 v[210:213], v233 offset:54272
	ds_read_b128 v[214:217], v233 offset:55296
	ds_read_b128 v[218:221], v233 offset:56320
	global_load_lds_dwordx4 v[164:165], off
	s_add_i32 m0, s78, 0x2000
	s_add_u32 s82, s94, 0x40080
	v_lshl_add_u64 v[164:165], v[192:193], 0, s[50:51]
	s_addc_u32 s83, s95, 0
	s_add_i32 s78, s79, s21
	global_load_lds_dwordx4 v[164:165], off
	v_lshl_add_u64 v[164:165], s[82:83], 0, v[198:199]
	s_mov_b32 m0, s78
	s_nop 0
	global_load_lds_dwordx4 v[164:165], off
	v_lshl_add_u64 v[164:165], s[82:83], 0, v[190:191]
	s_add_i32 m0, s78, 0x2000
	s_nop 0
	global_load_lds_dwordx4 v[164:165], off
	v_lshl_add_u64 v[164:165], v[234:235], 0, s[50:51]
	s_mov_b32 m0, s92
	s_nop 0
	global_load_lds_dwordx4 v[164:165], off
	v_lshl_add_u64 v[164:165], v[236:237], 0, s[50:51]
	s_mov_b32 m0, s93
	s_nop 0
	global_load_lds_dwordx4 v[164:165], off
	s_waitcnt vmcnt(8)
	s_waitcnt lgkmcnt(0)
	s_barrier
	s_setprio 1
	s_waitcnt lgkmcnt(0)
	v_mfma_f32_16x16x32_bf16 v[66:69], v[136:139], v[174:177], v[66:69]
	v_mfma_f32_16x16x32_bf16 v[62:65], v[144:147], v[174:177], v[62:65]
	v_mfma_f32_16x16x32_bf16 v[50:53], v[136:139], v[182:185], v[50:53]
	v_mfma_f32_16x16x32_bf16 v[46:49], v[144:147], v[182:185], v[46:49]
	v_mfma_f32_16x16x32_bf16 v[34:37], v[136:139], v[206:209], v[34:37]
	v_mfma_f32_16x16x32_bf16 v[30:33], v[144:147], v[206:209], v[30:33]
	v_mfma_f32_16x16x32_bf16 v[18:21], v[136:139], v[214:217], v[18:21]
	v_mfma_f32_16x16x32_bf16 v[14:17], v[144:147], v[214:217], v[14:17]
	v_mfma_f32_16x16x32_bf16 v[66:69], v[140:143], v[178:181], v[66:69]
	v_mfma_f32_16x16x32_bf16 v[62:65], v[148:151], v[178:181], v[62:65]
	v_mfma_f32_16x16x32_bf16 v[50:53], v[140:143], v[186:189], v[50:53]
	v_mfma_f32_16x16x32_bf16 v[46:49], v[148:151], v[186:189], v[46:49]
	v_mfma_f32_16x16x32_bf16 v[34:37], v[140:143], v[210:213], v[34:37]
	v_mfma_f32_16x16x32_bf16 v[30:33], v[148:151], v[210:213], v[30:33]
	v_mfma_f32_16x16x32_bf16 v[18:21], v[140:143], v[218:221], v[18:21]
	v_mfma_f32_16x16x32_bf16 v[14:17], v[148:151], v[218:221], v[14:17]
	s_setprio 0
	s_setprio 1
	v_mfma_f32_16x16x32_bf16 v[58:61], v[152:155], v[174:177], v[58:61]
	v_mfma_f32_16x16x32_bf16 v[54:57], v[160:163], v[174:177], v[54:57]
	v_mfma_f32_16x16x32_bf16 v[42:45], v[152:155], v[182:185], v[42:45]
	v_mfma_f32_16x16x32_bf16 v[38:41], v[160:163], v[182:185], v[38:41]
	v_mfma_f32_16x16x32_bf16 v[26:29], v[152:155], v[206:209], v[26:29]
	v_mfma_f32_16x16x32_bf16 v[22:25], v[160:163], v[206:209], v[22:25]
	v_mfma_f32_16x16x32_bf16 v[10:13], v[152:155], v[214:217], v[10:13]
	v_mfma_f32_16x16x32_bf16 v[6:9], v[160:163], v[214:217], v[6:9]
	v_mfma_f32_16x16x32_bf16 v[58:61], v[156:159], v[178:181], v[58:61]
	v_mfma_f32_16x16x32_bf16 v[54:57], v[170:173], v[178:181], v[54:57]
	v_mfma_f32_16x16x32_bf16 v[42:45], v[156:159], v[186:189], v[42:45]
	v_mfma_f32_16x16x32_bf16 v[38:41], v[170:173], v[186:189], v[38:41]
	v_mfma_f32_16x16x32_bf16 v[26:29], v[156:159], v[210:213], v[26:29]
	v_mfma_f32_16x16x32_bf16 v[22:25], v[170:173], v[210:213], v[22:25]
	s_setprio 2
	s_barrier
	v_mfma_f32_16x16x32_bf16 v[10:13], v[156:159], v[218:221], v[10:13]
	v_mfma_f32_16x16x32_bf16 v[6:9], v[170:173], v[218:221], v[6:9]
	s_setprio 0
	s_add_u32 s80, s80, 0x100
	s_addc_u32 s81, s81, 0
	s_add_u32 s54, s54, 0x100
	s_addc_u32 s55, s55, 0
	s_add_u32 s48, s48, 0xffffff00
	s_addc_u32 s49, s49, -1
	v_lshl_add_u64 v[134:135], v[134:135], 0, s[24:25]
	s_cmp_ge_u32 s16, s97
	v_lshl_add_u64 v[4:5], v[4:5], 0, s[24:25]
	s_cbranch_scc0 .LBB0_603
	s_mov_b32 s16, 8
	s_mov_b64 s[44:45], 0
	s_mov_b64 s[48:49], -1
	s_and_b64 vcc, exec, s[46:47]
	s_cbranch_vccz .LBB0_600
	s_and_b64 vcc, exec, s[8:9]
	s_cbranch_vccz .LBB0_607
	s_barrier

; #define PG8_STAGE(bufoff, gbase, voff) do { _Pragma("unroll") for (int _i = 0; _i < 2; ++_i) \
;         __builtin_amdgcn_global_load_lds((const unsigned*)((const char*)(gbase) + (voff)[_i]), (PG8_LAS unsigned*)(lds + (bufoff) + ldsw + _i * 8192), 16, 0, 0); } while (0)
; #define PG8_LDA(dst, b, h) do { _Pragma("unroll") for (int m = 0; m < 4; ++m) _Pragma("unroll") for (int k = 0; k < 2; ++k) dst[m][k] = *(const PG8_LAS bf16x8*)(lds + PG8_SA(b, h) + aoff + m * 2048 + k * 1024); } while (0)
; #define PG8_LDB(dst, b, h) do { _Pragma("unroll") for (int n = 0; n < 2; ++n) _Pragma("unroll") for (int k = 0; k < 2; ++k) dst[n][k] = *(const PG8_LAS bf16x8*)(lds + PG8_SB(b, h) + boff + n * 2048 + k * 1024); } while (0)
; #define PG8_WAIT_V(n) asm volatile("s_waitcnt vmcnt(" #n ")" ::: "memory")
; #define PG8_WAIT_L(n) asm volatile("s_waitcnt lgkmcnt(" #n ")" ::: "memory")
; #define PG8_BAR __builtin_amdgcn_s_barrier()
; template <class Epi, class Sched, bool ALIGN_EPI = false, bool SP2 = false>
; __device__ __forceinline__ void gemm_phase(PG8_LAS unsigned char* lds, const Gemm g, const Sched& S, const Epi& E) {
;     ...
;         for (int th = 0; th < (Epi::HAS_MID ? 2 : 1); ++th) { const int tlo = Epi::HAS_MID ? th * (nt / 2) : 0, thi = Epi::HAS_MID ? tlo + nt / 2 : nt;
;         if constexpr (Epi::HAS_MID) { if (th == 1) { PG8_SCHED; E.mid(acc, cur, wr, wc, fr, fq); PG8_SCHED; } }
;         for (int t = tlo; t < thi; t += 2) {
;             const bool last = (t == nt - 2);
;             const char* a1 = cA + (size_t)(t + 1) * kstep;
;             const char* a2 = last ? nA : cA + (size_t)(t + 2) * kstep; const char* b2 = last ? nB : cB + (size_t)(t + 2) * kstep;
;             const char* a3 = a2 + kstep; const char* b3 = b2 + kstep;
;             if (last && has_next) S.a_ready(nxt);
;             if constexpr (SP2) {
;             PG8_LDB(B0, 0, 0); PG8_LDB(B1, 0, 1); PG8_SCHED; PG8_LDA(At, 0, 0); PG8_STAGE(PG8_SA(1, 1), a1 + hstep, voffA);
;             PG8_WAIT_V(8); PG8_WAIT_L(0); PG8_BAR; PG8_MMA(0, 0, At, B0); PG8_MMA(0, 1, At, B1); PG8_BAR; PG8_SCHED;
;             PG8_LDA(At, 0, 1); PG8_STAGE(PG8_SB(0, 0), b2, voffB); PG8_STAGE(PG8_SB(0, 1), b2 + hstep, voffB); PG8_STAGE(PG8_SA(0, 0), a2, voffA);
;             PG8_WAIT_V(8); PG8_WAIT_L(0); PG8_BAR; PG8_MMA(1, 0, At, B0); PG8_MMA(1, 1, At, B1); PG8_BAR; PG8_SCHED;
.LBB0_724:
	s_add_u32 s76, vcc_lo, 0xfffc0080
	s_addc_u32 s77, vcc_hi, -1
	s_add_i32 s78, 0, 0x10000
	s_cmp_eq_u32 s39, 12
	s_cselect_b32 s93, s11, s77
	s_cselect_b32 s92, s13, s76
	s_cselect_b32 s95, s23, s38
	s_cselect_b32 s94, s27, s37
	s_add_i32 s79, 0, 0x14000
	v_add_u32_e32 v144, s78, v184
	v_add_u32_e32 v168, s79, v184
	ds_read_b128 v[132:135], v144
	ds_read_b128 v[136:139], v144 offset:1024
	ds_read_b128 v[140:143], v144 offset:2048
	ds_read_b128 v[144:147], v144 offset:3072
	ds_read_b128 v[148:151], v168
	ds_read_b128 v[152:155], v168 offset:1024
	ds_read_b128 v[164:167], v168 offset:2048
	ds_read_b128 v[168:171], v168 offset:3072
	v_lshl_add_u64 v[192:193], vcc, 0, v[160:161]
	s_add_i32 m0, s20, 0xc000
	ds_read_b128 v[172:175], v189
	ds_read_b128 v[176:179], v189 offset:1024
	ds_read_b128 v[180:183], v189 offset:2048
	ds_read_b128 v[198:201], v189 offset:3072
	ds_read_b128 v[202:205], v189 offset:4096
	ds_read_b128 v[206:209], v189 offset:5120
	ds_read_b128 v[210:213], v189 offset:6144
	ds_read_b128 v[214:217], v189 offset:7168
	global_load_lds_dwordx4 v[192:193], off
	v_lshl_add_u64 v[192:193], vcc, 0, v[162:163]
	s_add_i32 m0, s20, 0xe000
	s_nop 0
	global_load_lds_dwordx4 v[192:193], off
	s_waitcnt vmcnt(8)
	s_waitcnt lgkmcnt(0)
	s_barrier
	s_setprio 1
	s_waitcnt lgkmcnt(0)
	v_mfma_f32_16x16x32_bf16 v[60:63], v[132:135], v[172:175], v[60:63]
	v_mfma_f32_16x16x32_bf16 v[64:67], v[140:143], v[172:175], v[64:67]
	v_mfma_f32_16x16x32_bf16 v[92:95], v[132:135], v[180:183], v[92:95]
	v_mfma_f32_16x16x32_bf16 v[96:99], v[140:143], v[180:183], v[96:99]
	v_mfma_f32_16x16x32_bf16 v[116:119], v[132:135], v[202:205], v[116:119]
	v_mfma_f32_16x16x32_bf16 v[120:123], v[140:143], v[202:205], v[120:123]
	v_mfma_f32_16x16x32_bf16 v[112:115], v[132:135], v[210:213], v[112:115]
	v_mfma_f32_16x16x32_bf16 v[108:111], v[140:143], v[210:213], v[108:111]
	v_mfma_f32_16x16x32_bf16 v[60:63], v[136:139], v[176:179], v[60:63]
	v_mfma_f32_16x16x32_bf16 v[64:67], v[144:147], v[176:179], v[64:67]
	v_mfma_f32_16x16x32_bf16 v[92:95], v[136:139], v[198:201], v[92:95]
	v_mfma_f32_16x16x32_bf16 v[96:99], v[144:147], v[198:201], v[96:99]
	v_mfma_f32_16x16x32_bf16 v[116:119], v[136:139], v[206:209], v[116:119]
	v_mfma_f32_16x16x32_bf16 v[120:123], v[144:147], v[206:209], v[120:123]
	v_mfma_f32_16x16x32_bf16 v[112:115], v[136:139], v[214:217], v[112:115]
	v_mfma_f32_16x16x32_bf16 v[108:111], v[144:147], v[214:217], v[108:111]
	s_setprio 0
	s_setprio 1
	v_mfma_f32_16x16x32_bf16 v[72:75], v[148:151], v[172:175], v[72:75]
	v_mfma_f32_16x16x32_bf16 v[76:79], v[164:167], v[172:175], v[76:79]
	v_mfma_f32_16x16x32_bf16 v[100:103], v[148:151], v[180:183], v[100:103]
	v_mfma_f32_16x16x32_bf16 v[104:107], v[164:167], v[180:183], v[104:107]
	v_mfma_f32_16x16x32_bf16 v[124:127], v[148:151], v[202:205], v[124:127]
	v_mfma_f32_16x16x32_bf16 v[128:131], v[164:167], v[202:205], v[128:131]
	v_mfma_f32_16x16x32_bf16 v[88:91], v[148:151], v[210:213], v[88:91]
	v_mfma_f32_16x16x32_bf16 v[84:87], v[164:167], v[210:213], v[84:87]
	v_mfma_f32_16x16x32_bf16 v[72:75], v[152:155], v[176:179], v[72:75]
	v_mfma_f32_16x16x32_bf16 v[76:79], v[168:171], v[176:179], v[76:79]
	v_mfma_f32_16x16x32_bf16 v[100:103], v[152:155], v[198:201], v[100:103]
	v_mfma_f32_16x16x32_bf16 v[104:107], v[168:171], v[198:201], v[104:107]
	v_mfma_f32_16x16x32_bf16 v[124:127], v[152:155], v[206:209], v[124:127]
	v_mfma_f32_16x16x32_bf16 v[128:131], v[168:171], v[206:209], v[128:131]
	s_setprio 2
	s_barrier
	v_mfma_f32_16x16x32_bf16 v[88:91], v[152:155], v[214:217], v[88:91]
	v_mfma_f32_16x16x32_bf16 v[84:87], v[168:171], v[214:217], v[84:87]
	s_setprio 0
	s_add_i32 s76, s78, s14
	v_lshl_add_u64 v[192:193], s[94:95], 0, v[2:3]
	s_mov_b32 m0, s76
	ds_read_b128 v[172:175], v189 offset:16384
	ds_read_b128 v[176:179], v189 offset:17408
	ds_read_b128 v[180:183], v189 offset:18432
	ds_read_b128 v[198:201], v189 offset:19456
	ds_read_b128 v[202:205], v189 offset:20480
	ds_read_b128 v[206:209], v189 offset:21504
	ds_read_b128 v[210:213], v189 offset:22528
	ds_read_b128 v[214:217], v189 offset:23552
	global_load_lds_dwordx4 v[192:193], off
	s_add_i32 m0, s76, 0x2000
	s_add_u32 s76, s94, 0x40000
	v_lshl_add_u64 v[218:219], s[94:95], 0, v[156:157]
	s_addc_u32 s77, s95, 0
	s_add_i32 s78, s79, s14
	global_load_lds_dwordx4 v[218:219], off
	v_lshl_add_u64 v[220:221], s[76:77], 0, v[2:3]
	s_mov_b32 m0, s78
	v_lshl_add_u64 v[228:229], s[92:93], 0, v[156:157]
	global_load_lds_dwordx4 v[220:221], off
	v_lshl_add_u64 v[220:221], s[76:77], 0, v[156:157]
	s_add_i32 m0, s78, 0x2000
	s_nop 0
	global_load_lds_dwordx4 v[220:221], off
	v_lshl_add_u64 v[220:221], s[92:93], 0, v[2:3]
	s_mov_b32 m0, s20
	s_nop 0
	global_load_lds_dwordx4 v[220:221], off
	s_mov_b32 m0, s21
	s_nop 0
	global_load_lds_dwordx4 v[228:229], off
	s_waitcnt vmcnt(8)
	s_waitcnt lgkmcnt(0)
	s_barrier
; #define PG8_STAGE(bufoff, gbase, voff) do { _Pragma("unroll") for (int _i = 0; _i < 2; ++_i) \
;         __builtin_amdgcn_global_load_lds((const unsigned*)((const char*)(gbase) + (voff)[_i]), (PG8_LAS unsigned*)(lds + (bufoff) + ldsw + _i * 8192), 16, 0, 0); } while (0)
; #define PG8_LDA(dst, b, h) do { _Pragma("unroll") for (int m = 0; m < 4; ++m) _Pragma("unroll") for (int k = 0; k < 2; ++k) dst[m][k] = *(const PG8_LAS bf16x8*)(lds + PG8_SA(b, h) + aoff + m * 2048 + k * 1024); } while (0)
; #define PG8_LDB(dst, b, h) do { _Pragma("unroll") for (int n = 0; n < 2; ++n) _Pragma("unroll") for (int k = 0; k < 2; ++k) dst[n][k] = *(const PG8_LAS bf16x8*)(lds + PG8_SB(b, h) + boff + n * 2048 + k * 1024); } while (0)
; #define PG8_MMA(ai, bj, At, Bt) do { __builtin_amdgcn_s_setprio(1); _Pragma("unroll") for (int m = 0; m < 4; ++m) _Pragma("unroll") for (int n = 0; n < 2; ++n) _Pragma("unroll") for (int k = 0; k < 2; ++k) \
;         acc[ai][bj][m][n] = __builtin_amdgcn_mfma_f32_16x16x32_bf16(Bt[n][k], At[m][k], acc[ai][bj][m][n], 0, 0, 0); __builtin_amdgcn_s_setprio(0); } while (0)
; #define PG8_WAIT_V(n) asm volatile("s_waitcnt vmcnt(" #n ")" ::: "memory")
; #define PG8_WAIT_L(n) asm volatile("s_waitcnt lgkmcnt(" #n ")" ::: "memory")
; #define PG8_BAR __builtin_amdgcn_s_barrier()
; #define PG8_SCHED __builtin_amdgcn_sched_barrier(0)
; template <class Epi, class Sched, bool ALIGN_EPI = false, bool SP2 = false>
; __device__ __forceinline__ void gemm_phase(PG8_LAS unsigned char* lds, const Gemm g, const Sched& S, const Epi& E) {
;     ...
;             PG8_WAIT_V(8); PG8_WAIT_L(0); PG8_BAR; PG8_MMA(1, 0, At, B0); PG8_MMA(1, 1, At, B1); PG8_BAR; PG8_SCHED;
;             PG8_LDB(B0, 1, 0); PG8_LDB(B1, 1, 1); PG8_SCHED; PG8_LDA(At, 1, 0); PG8_STAGE(PG8_SA(0, 1), a2 + hstep, voffA);
;             PG8_WAIT_V(8); PG8_WAIT_L(0); PG8_BAR; PG8_MMA(0, 0, At, B0); PG8_MMA(0, 1, At, B1); PG8_BAR; PG8_SCHED;
	s_setprio 1
	s_waitcnt lgkmcnt(0)
	v_mfma_f32_16x16x32_bf16 v[80:83], v[132:135], v[172:175], v[80:83]
	v_mfma_f32_16x16x32_bf16 v[68:71], v[140:143], v[172:175], v[68:71]
	v_mfma_f32_16x16x32_bf16 v[48:51], v[132:135], v[180:183], v[48:51]
	v_mfma_f32_16x16x32_bf16 v[44:47], v[140:143], v[180:183], v[44:47]
	v_mfma_f32_16x16x32_bf16 v[32:35], v[132:135], v[202:205], v[32:35]
	v_mfma_f32_16x16x32_bf16 v[28:31], v[140:143], v[202:205], v[28:31]
	v_mfma_f32_16x16x32_bf16 v[16:19], v[132:135], v[210:213], v[16:19]
	v_mfma_f32_16x16x32_bf16 v[12:15], v[140:143], v[210:213], v[12:15]
	v_mfma_f32_16x16x32_bf16 v[80:83], v[136:139], v[176:179], v[80:83]
	v_mfma_f32_16x16x32_bf16 v[68:71], v[144:147], v[176:179], v[68:71]
	v_mfma_f32_16x16x32_bf16 v[48:51], v[136:139], v[198:201], v[48:51]
	v_mfma_f32_16x16x32_bf16 v[44:47], v[144:147], v[198:201], v[44:47]
	v_mfma_f32_16x16x32_bf16 v[32:35], v[136:139], v[206:209], v[32:35]
	v_mfma_f32_16x16x32_bf16 v[28:31], v[144:147], v[206:209], v[28:31]
	v_mfma_f32_16x16x32_bf16 v[16:19], v[136:139], v[214:217], v[16:19]
	v_mfma_f32_16x16x32_bf16 v[12:15], v[144:147], v[214:217], v[12:15]
	s_setprio 0
	s_setprio 1
	v_mfma_f32_16x16x32_bf16 v[56:59], v[148:151], v[172:175], v[56:59]
	v_mfma_f32_16x16x32_bf16 v[52:55], v[164:167], v[172:175], v[52:55]
	v_mfma_f32_16x16x32_bf16 v[40:43], v[148:151], v[180:183], v[40:43]
	v_mfma_f32_16x16x32_bf16 v[36:39], v[164:167], v[180:183], v[36:39]
	v_mfma_f32_16x16x32_bf16 v[24:27], v[148:151], v[202:205], v[24:27]
	v_mfma_f32_16x16x32_bf16 v[20:23], v[164:167], v[202:205], v[20:23]
	v_mfma_f32_16x16x32_bf16 v[8:11], v[148:151], v[210:213], v[8:11]
	v_mfma_f32_16x16x32_bf16 v[4:7], v[164:167], v[210:213], v[4:7]
	v_mfma_f32_16x16x32_bf16 v[56:59], v[152:155], v[176:179], v[56:59]
	v_mfma_f32_16x16x32_bf16 v[52:55], v[168:171], v[176:179], v[52:55]
	v_mfma_f32_16x16x32_bf16 v[40:43], v[152:155], v[198:201], v[40:43]
	v_mfma_f32_16x16x32_bf16 v[36:39], v[168:171], v[198:201], v[36:39]
	v_mfma_f32_16x16x32_bf16 v[24:27], v[152:155], v[206:209], v[24:27]
	v_mfma_f32_16x16x32_bf16 v[20:23], v[168:171], v[206:209], v[20:23]
	s_setprio 2
	s_barrier
	v_mfma_f32_16x16x32_bf16 v[8:11], v[152:155], v[214:217], v[8:11]
	v_mfma_f32_16x16x32_bf16 v[4:7], v[168:171], v[214:217], v[4:7]
	s_setprio 0
	s_add_i32 s78, 0, 0x18000
	s_add_i32 s79, 0, 0x1c000
	v_add_u32_e32 v144, s78, v184
	v_add_u32_e32 v168, s79, v184
	ds_read_b128 v[132:135], v144
	ds_read_b128 v[136:139], v144 offset:1024
	ds_read_b128 v[140:143], v144 offset:2048
	ds_read_b128 v[144:147], v144 offset:3072
	ds_read_b128 v[148:151], v168
	ds_read_b128 v[152:155], v168 offset:1024
	ds_read_b128 v[164:167], v168 offset:2048
	ds_read_b128 v[168:171], v168 offset:3072
	s_add_u32 s76, s92, 0x40000
	s_addc_u32 s77, s93, 0
	s_mov_b32 m0, s28
	v_lshl_add_u64 v[230:231], s[76:77], 0, v[2:3]
	ds_read_b128 v[172:175], v189 offset:32768
	ds_read_b128 v[176:179], v189 offset:33792
	ds_read_b128 v[180:183], v189 offset:34816
	ds_read_b128 v[198:201], v189 offset:35840
	ds_read_b128 v[202:205], v189 offset:36864
	ds_read_b128 v[206:209], v189 offset:37888
	ds_read_b128 v[210:213], v189 offset:38912
	ds_read_b128 v[214:217], v189 offset:39936
	global_load_lds_dwordx4 v[230:231], off
	v_lshl_add_u64 v[230:231], s[76:77], 0, v[156:157]
	s_mov_b32 m0, s29
	s_nop 0
	global_load_lds_dwordx4 v[230:231], off
	s_waitcnt vmcnt(8)
	s_waitcnt lgkmcnt(0)
	s_barrier
	s_setprio 1
	s_waitcnt lgkmcnt(0)
	v_mfma_f32_16x16x32_bf16 v[60:63], v[132:135], v[172:175], v[60:63]
	v_mfma_f32_16x16x32_bf16 v[64:67], v[140:143], v[172:175], v[64:67]
	v_mfma_f32_16x16x32_bf16 v[92:95], v[132:135], v[180:183], v[92:95]
	v_mfma_f32_16x16x32_bf16 v[96:99], v[140:143], v[180:183], v[96:99]
	v_mfma_f32_16x16x32_bf16 v[116:119], v[132:135], v[202:205], v[116:119]
	v_mfma_f32_16x16x32_bf16 v[120:123], v[140:143], v[202:205], v[120:123]
	v_mfma_f32_16x16x32_bf16 v[112:115], v[132:135], v[210:213], v[112:115]
	v_mfma_f32_16x16x32_bf16 v[108:111], v[140:143], v[210:213], v[108:111]
	v_mfma_f32_16x16x32_bf16 v[60:63], v[136:139], v[176:179], v[60:63]
	v_mfma_f32_16x16x32_bf16 v[64:67], v[144:147], v[176:179], v[64:67]
	v_mfma_f32_16x16x32_bf16 v[92:95], v[136:139], v[198:201], v[92:95]
	v_mfma_f32_16x16x32_bf16 v[96:99], v[144:147], v[198:201], v[96:99]
	v_mfma_f32_16x16x32_bf16 v[116:119], v[136:139], v[206:209], v[116:119]
	v_mfma_f32_16x16x32_bf16 v[120:123], v[144:147], v[206:209], v[120:123]
	v_mfma_f32_16x16x32_bf16 v[112:115], v[136:139], v[214:217], v[112:115]
	v_mfma_f32_16x16x32_bf16 v[108:111], v[144:147], v[214:217], v[108:111]
	s_setprio 0
	s_setprio 1
	v_mfma_f32_16x16x32_bf16 v[72:75], v[148:151], v[172:175], v[72:75]
	v_mfma_f32_16x16x32_bf16 v[76:79], v[164:167], v[172:175], v[76:79]
	v_mfma_f32_16x16x32_bf16 v[100:103], v[148:151], v[180:183], v[100:103]
	v_mfma_f32_16x16x32_bf16 v[104:107], v[164:167], v[180:183], v[104:107]
	v_mfma_f32_16x16x32_bf16 v[124:127], v[148:151], v[202:205], v[124:127]
	v_mfma_f32_16x16x32_bf16 v[128:131], v[164:167], v[202:205], v[128:131]
	v_mfma_f32_16x16x32_bf16 v[88:91], v[148:151], v[210:213], v[88:91]
	v_mfma_f32_16x16x32_bf16 v[84:87], v[164:167], v[210:213], v[84:87]
	v_mfma_f32_16x16x32_bf16 v[72:75], v[152:155], v[176:179], v[72:75]
	v_mfma_f32_16x16x32_bf16 v[76:79], v[168:171], v[176:179], v[76:79]
	v_mfma_f32_16x16x32_bf16 v[100:103], v[152:155], v[198:201], v[100:103]
	v_mfma_f32_16x16x32_bf16 v[104:107], v[168:171], v[198:201], v[104:107]
	v_mfma_f32_16x16x32_bf16 v[124:127], v[152:155], v[206:209], v[124:127]
	v_mfma_f32_16x16x32_bf16 v[128:131], v[168:171], v[206:209], v[128:131]
	s_setprio 2
	s_barrier
; #define PG8_STAGE(bufoff, gbase, voff) do { _Pragma("unroll") for (int _i = 0; _i < 2; ++_i) \
;         __builtin_amdgcn_global_load_lds((const unsigned*)((const char*)(gbase) + (voff)[_i]), (PG8_LAS unsigned*)(lds + (bufoff) + ldsw + _i * 8192), 16, 0, 0); } while (0)
; #define PG8_LDA(dst, b, h) do { _Pragma("unroll") for (int m = 0; m < 4; ++m) _Pragma("unroll") for (int k = 0; k < 2; ++k) dst[m][k] = *(const PG8_LAS bf16x8*)(lds + PG8_SA(b, h) + aoff + m * 2048 + k * 1024); } while (0)
; #define PG8_MMA(ai, bj, At, Bt) do { __builtin_amdgcn_s_setprio(1); _Pragma("unroll") for (int m = 0; m < 4; ++m) _Pragma("unroll") for (int n = 0; n < 2; ++n) _Pragma("unroll") for (int k = 0; k < 2; ++k) \
;         acc[ai][bj][m][n] = __builtin_amdgcn_mfma_f32_16x16x32_bf16(Bt[n][k], At[m][k], acc[ai][bj][m][n], 0, 0, 0); __builtin_amdgcn_s_setprio(0); } while (0)
; #define PG8_WAIT_V(n) asm volatile("s_waitcnt vmcnt(" #n ")" ::: "memory")
; #define PG8_WAIT_L(n) asm volatile("s_waitcnt lgkmcnt(" #n ")" ::: "memory")
; #define PG8_BAR __builtin_amdgcn_s_barrier()
; #define PG8_SCHED __builtin_amdgcn_sched_barrier(0)
; template <class Epi, class Sched, bool ALIGN_EPI = false, bool SP2 = false>
; __device__ __forceinline__ void gemm_phase(PG8_LAS unsigned char* lds, const Gemm g, const Sched& S, const Epi& E) {
;     ...
;             PG8_LDA(At, 1, 1); PG8_STAGE(PG8_SB(1, 0), b3, voffB); PG8_STAGE(PG8_SB(1, 1), b3 + hstep, voffB); PG8_STAGE(PG8_SA(1, 0), a3, voffA);
;             PG8_WAIT_V(8); PG8_WAIT_L(0); PG8_BAR; PG8_MMA(1, 0, At, B0); PG8_MMA(1, 1, At, B1); PG8_BAR; PG8_SCHED;
;     ...
;         if constexpr (ALIGN_EPI) { if (wr == 0) PG8_BAR; }
	v_mfma_f32_16x16x32_bf16 v[88:91], v[152:155], v[214:217], v[88:91]
	v_mfma_f32_16x16x32_bf16 v[84:87], v[168:171], v[214:217], v[84:87]
	s_setprio 0
	s_add_i32 s76, s78, s14
	v_lshl_add_u64 v[192:193], v[192:193], 0, s[50:51]
	s_mov_b32 m0, s76
	ds_read_b128 v[172:175], v189 offset:49152
	ds_read_b128 v[176:179], v189 offset:50176
	ds_read_b128 v[180:183], v189 offset:51200
	ds_read_b128 v[198:201], v189 offset:52224
	ds_read_b128 v[202:205], v189 offset:53248
	ds_read_b128 v[206:209], v189 offset:54272
	ds_read_b128 v[210:213], v189 offset:55296
	ds_read_b128 v[214:217], v189 offset:56320
	global_load_lds_dwordx4 v[192:193], off
	s_add_i32 m0, s76, 0x2000
	s_add_u32 s76, s94, 0x40080
	v_lshl_add_u64 v[192:193], v[218:219], 0, s[50:51]
	s_addc_u32 s77, s95, 0
	s_add_i32 s78, s79, s14
	global_load_lds_dwordx4 v[192:193], off
	v_lshl_add_u64 v[192:193], s[76:77], 0, v[2:3]
	s_mov_b32 m0, s78
	s_nop 0
	global_load_lds_dwordx4 v[192:193], off
	v_lshl_add_u64 v[192:193], s[76:77], 0, v[156:157]
	s_add_i32 m0, s78, 0x2000
	s_nop 0
	global_load_lds_dwordx4 v[192:193], off
	v_lshl_add_u64 v[192:193], v[220:221], 0, s[50:51]
	s_mov_b32 m0, s30
	s_nop 0
	global_load_lds_dwordx4 v[192:193], off
	v_lshl_add_u64 v[192:193], v[228:229], 0, s[50:51]
	s_mov_b32 m0, s31
	s_nop 0
	global_load_lds_dwordx4 v[192:193], off
	s_waitcnt vmcnt(8)
	s_waitcnt lgkmcnt(0)
	s_barrier
	s_setprio 1
	s_waitcnt lgkmcnt(0)
	v_mfma_f32_16x16x32_bf16 v[80:83], v[132:135], v[172:175], v[80:83]
	v_mfma_f32_16x16x32_bf16 v[68:71], v[140:143], v[172:175], v[68:71]
	v_mfma_f32_16x16x32_bf16 v[48:51], v[132:135], v[180:183], v[48:51]
	v_mfma_f32_16x16x32_bf16 v[44:47], v[140:143], v[180:183], v[44:47]
	v_mfma_f32_16x16x32_bf16 v[32:35], v[132:135], v[202:205], v[32:35]
	v_mfma_f32_16x16x32_bf16 v[28:31], v[140:143], v[202:205], v[28:31]
	v_mfma_f32_16x16x32_bf16 v[16:19], v[132:135], v[210:213], v[16:19]
	v_mfma_f32_16x16x32_bf16 v[12:15], v[140:143], v[210:213], v[12:15]
	v_mfma_f32_16x16x32_bf16 v[80:83], v[136:139], v[176:179], v[80:83]
	v_mfma_f32_16x16x32_bf16 v[68:71], v[144:147], v[176:179], v[68:71]
	v_mfma_f32_16x16x32_bf16 v[48:51], v[136:139], v[198:201], v[48:51]
	v_mfma_f32_16x16x32_bf16 v[44:47], v[144:147], v[198:201], v[44:47]
	v_mfma_f32_16x16x32_bf16 v[32:35], v[136:139], v[206:209], v[32:35]
	v_mfma_f32_16x16x32_bf16 v[28:31], v[144:147], v[206:209], v[28:31]
	v_mfma_f32_16x16x32_bf16 v[16:19], v[136:139], v[214:217], v[16:19]
	v_mfma_f32_16x16x32_bf16 v[12:15], v[144:147], v[214:217], v[12:15]
	s_setprio 0
	s_setprio 1
	v_mfma_f32_16x16x32_bf16 v[56:59], v[148:151], v[172:175], v[56:59]
	v_mfma_f32_16x16x32_bf16 v[52:55], v[164:167], v[172:175], v[52:55]
	v_mfma_f32_16x16x32_bf16 v[40:43], v[148:151], v[180:183], v[40:43]
	v_mfma_f32_16x16x32_bf16 v[36:39], v[164:167], v[180:183], v[36:39]
	v_mfma_f32_16x16x32_bf16 v[24:27], v[148:151], v[202:205], v[24:27]
	v_mfma_f32_16x16x32_bf16 v[20:23], v[164:167], v[202:205], v[20:23]
	v_mfma_f32_16x16x32_bf16 v[8:11], v[148:151], v[210:213], v[8:11]
	v_mfma_f32_16x16x32_bf16 v[4:7], v[164:167], v[210:213], v[4:7]
	v_mfma_f32_16x16x32_bf16 v[56:59], v[152:155], v[176:179], v[56:59]
	v_mfma_f32_16x16x32_bf16 v[52:55], v[168:171], v[176:179], v[52:55]
	v_mfma_f32_16x16x32_bf16 v[40:43], v[152:155], v[198:201], v[40:43]
	v_mfma_f32_16x16x32_bf16 v[36:39], v[168:171], v[198:201], v[36:39]
	v_mfma_f32_16x16x32_bf16 v[24:27], v[152:155], v[206:209], v[24:27]
	v_mfma_f32_16x16x32_bf16 v[20:23], v[168:171], v[206:209], v[20:23]
	s_setprio 2
	s_barrier
	v_mfma_f32_16x16x32_bf16 v[8:11], v[152:155], v[214:217], v[8:11]
	v_mfma_f32_16x16x32_bf16 v[4:7], v[168:171], v[214:217], v[4:7]
	s_setprio 0
	s_add_i32 s39, s39, 2
	s_add_u32 vcc_lo, vcc_lo, 0x100
	s_addc_u32 vcc_hi, vcc_hi, 0
	s_add_u32 s37, s37, 0x100
	s_addc_u32 s38, s38, 0
	s_cmp_gt_u32 s39, 13
	s_cbranch_scc0 .LBB0_724
	s_and_b64 vcc, exec, s[6:7]
	s_cbranch_vccz .LBB0_727
	s_barrier

; #define PG8_STAGE(bufoff, gbase, voff) do { _Pragma("unroll") for (int _i = 0; _i < 2; ++_i) \
;         __builtin_amdgcn_global_load_lds((const unsigned*)((const char*)(gbase) + (voff)[_i]), (PG8_LAS unsigned*)(lds + (bufoff) + ldsw + _i * 8192), 16, 0, 0); } while (0)
; #define PG8_LDA(dst, b, h) do { _Pragma("unroll") for (int m = 0; m < 4; ++m) _Pragma("unroll") for (int k = 0; k < 2; ++k) dst[m][k] = *(const PG8_LAS bf16x8*)(lds + PG8_SA(b, h) + aoff + m * 2048 + k * 1024); } while (0)
; #define PG8_LDB(dst, b, h) do { _Pragma("unroll") for (int n = 0; n < 2; ++n) _Pragma("unroll") for (int k = 0; k < 2; ++k) dst[n][k] = *(const PG8_LAS bf16x8*)(lds + PG8_SB(b, h) + boff + n * 2048 + k * 1024); } while (0)
; #define PG8_WAIT_V(n) asm volatile("s_waitcnt vmcnt(" #n ")" ::: "memory")
; #define PG8_WAIT_L(n) asm volatile("s_waitcnt lgkmcnt(" #n ")" ::: "memory")
; #define PG8_BAR __builtin_amdgcn_s_barrier()
; template <class Epi, class Sched, bool ALIGN_EPI = false, bool SP2 = false>
; __device__ __forceinline__ void gemm_phase(PG8_LAS unsigned char* lds, const Gemm g, const Sched& S, const Epi& E) {
;     ...
;         for (int th = 0; th < (Epi::HAS_MID ? 2 : 1); ++th) { const int tlo = Epi::HAS_MID ? th * (nt / 2) : 0, thi = Epi::HAS_MID ? tlo + nt / 2 : nt;
;         if constexpr (Epi::HAS_MID) { if (th == 1) { PG8_SCHED; E.mid(acc, cur, wr, wc, fr, fq); PG8_SCHED; } }
;         for (int t = tlo; t < thi; t += 2) {
;             const bool last = (t == nt - 2);
;             const char* a1 = cA + (size_t)(t + 1) * kstep;
;             const char* a2 = last ? nA : cA + (size_t)(t + 2) * kstep; const char* b2 = last ? nB : cB + (size_t)(t + 2) * kstep;
;             const char* a3 = a2 + kstep; const char* b3 = b2 + kstep;
;             if (last && has_next) S.a_ready(nxt);
;             if constexpr (SP2) {
;             PG8_LDB(B0, 0, 0); PG8_LDB(B1, 0, 1); PG8_SCHED; PG8_LDA(At, 0, 0); PG8_STAGE(PG8_SA(1, 1), a1 + hstep, voffA);
;             PG8_WAIT_V(8); PG8_WAIT_L(0); PG8_BAR; PG8_MMA(0, 0, At, B0); PG8_MMA(0, 1, At, B1); PG8_BAR; PG8_SCHED;
;             PG8_LDA(At, 0, 1); PG8_STAGE(PG8_SB(0, 0), b2, voffB); PG8_STAGE(PG8_SB(0, 1), b2 + hstep, voffB); PG8_STAGE(PG8_SA(0, 0), a2, voffA);
;             PG8_WAIT_V(8); PG8_WAIT_L(0); PG8_BAR; PG8_MMA(1, 0, At, B0); PG8_MMA(1, 1, At, B1); PG8_BAR; PG8_SCHED;
.LBB0_783:
	s_add_u32 s48, s80, 0xfffc0080
	s_addc_u32 s49, s81, -1
	s_add_i32 s78, 0, 0x10000
	s_cmp_eq_u32 s77, 12
	s_cselect_b32 s93, s11, s49
	s_cselect_b32 s92, s13, s48
	s_cselect_b32 s49, s23, s76
	s_cselect_b32 s48, s27, s37
	s_add_i32 s79, 0, 0x14000
	v_add_u32_e32 v144, s78, v214
	v_add_u32_e32 v160, s79, v214
	ds_read_b128 v[132:135], v144
	ds_read_b128 v[136:139], v144 offset:1024
	ds_read_b128 v[140:143], v144 offset:2048
	ds_read_b128 v[144:147], v144 offset:3072
	ds_read_b128 v[148:151], v160
	ds_read_b128 v[152:155], v160 offset:1024
	ds_read_b128 v[156:159], v160 offset:2048
	ds_read_b128 v[160:163], v160 offset:3072
	v_lshl_add_u64 v[192:193], s[80:81], 0, v[184:185]
	s_add_i32 m0, s20, 0xc000
	ds_read_b128 v[164:167], v219
	ds_read_b128 v[168:171], v219 offset:1024
	ds_read_b128 v[172:175], v219 offset:2048
	ds_read_b128 v[176:179], v219 offset:3072
	ds_read_b128 v[188:191], v219 offset:4096
	ds_read_b128 v[198:201], v219 offset:5120
	ds_read_b128 v[202:205], v219 offset:6144
	ds_read_b128 v[206:209], v219 offset:7168
	global_load_lds_dwordx4 v[192:193], off
	v_lshl_add_u64 v[192:193], s[80:81], 0, v[186:187]
	s_add_i32 m0, s20, 0xe000
	s_nop 0
	global_load_lds_dwordx4 v[192:193], off
	s_waitcnt vmcnt(8)
	s_waitcnt lgkmcnt(0)
	s_barrier
	s_setprio 1
	s_waitcnt lgkmcnt(0)
	v_mfma_f32_16x16x32_bf16 v[68:71], v[132:135], v[164:167], v[68:71]
	v_mfma_f32_16x16x32_bf16 v[72:75], v[140:143], v[164:167], v[72:75]
	v_mfma_f32_16x16x32_bf16 v[84:87], v[132:135], v[172:175], v[84:87]
	v_mfma_f32_16x16x32_bf16 v[88:91], v[140:143], v[172:175], v[88:91]
	v_mfma_f32_16x16x32_bf16 v[116:119], v[132:135], v[188:191], v[116:119]
	v_mfma_f32_16x16x32_bf16 v[124:127], v[140:143], v[188:191], v[124:127]
	v_mfma_f32_16x16x32_bf16 v[128:131], v[132:135], v[202:205], v[128:131]
	v_mfma_f32_16x16x32_bf16 v[120:123], v[140:143], v[202:205], v[120:123]
	v_mfma_f32_16x16x32_bf16 v[68:71], v[136:139], v[168:171], v[68:71]
	v_mfma_f32_16x16x32_bf16 v[72:75], v[144:147], v[168:171], v[72:75]
	v_mfma_f32_16x16x32_bf16 v[84:87], v[136:139], v[176:179], v[84:87]
	v_mfma_f32_16x16x32_bf16 v[88:91], v[144:147], v[176:179], v[88:91]
	v_mfma_f32_16x16x32_bf16 v[116:119], v[136:139], v[198:201], v[116:119]
	v_mfma_f32_16x16x32_bf16 v[124:127], v[144:147], v[198:201], v[124:127]
	v_mfma_f32_16x16x32_bf16 v[128:131], v[136:139], v[206:209], v[128:131]
	v_mfma_f32_16x16x32_bf16 v[120:123], v[144:147], v[206:209], v[120:123]
	s_setprio 0
	s_setprio 1
	v_mfma_f32_16x16x32_bf16 v[76:79], v[148:151], v[164:167], v[76:79]
	v_mfma_f32_16x16x32_bf16 v[80:83], v[156:159], v[164:167], v[80:83]
	v_mfma_f32_16x16x32_bf16 v[96:99], v[148:151], v[172:175], v[96:99]
	v_mfma_f32_16x16x32_bf16 v[100:103], v[156:159], v[172:175], v[100:103]
	v_mfma_f32_16x16x32_bf16 v[108:111], v[148:151], v[188:191], v[108:111]
	v_mfma_f32_16x16x32_bf16 v[112:115], v[156:159], v[188:191], v[112:115]
	v_mfma_f32_16x16x32_bf16 v[104:107], v[148:151], v[202:205], v[104:107]
	v_mfma_f32_16x16x32_bf16 v[92:95], v[156:159], v[202:205], v[92:95]
	v_mfma_f32_16x16x32_bf16 v[76:79], v[152:155], v[168:171], v[76:79]
	v_mfma_f32_16x16x32_bf16 v[80:83], v[160:163], v[168:171], v[80:83]
	v_mfma_f32_16x16x32_bf16 v[96:99], v[152:155], v[176:179], v[96:99]
	v_mfma_f32_16x16x32_bf16 v[100:103], v[160:163], v[176:179], v[100:103]
	v_mfma_f32_16x16x32_bf16 v[108:111], v[152:155], v[198:201], v[108:111]
	v_mfma_f32_16x16x32_bf16 v[112:115], v[160:163], v[198:201], v[112:115]
	s_setprio 2
	s_barrier
	v_mfma_f32_16x16x32_bf16 v[104:107], v[152:155], v[206:209], v[104:107]
	v_mfma_f32_16x16x32_bf16 v[92:95], v[160:163], v[206:209], v[92:95]
	s_setprio 0
	s_add_i32 s78, s78, s14
	v_lshl_add_u64 v[192:193], s[48:49], 0, v[2:3]
	s_mov_b32 m0, s78
	ds_read_b128 v[164:167], v219 offset:16384
	ds_read_b128 v[168:171], v219 offset:17408
	ds_read_b128 v[172:175], v219 offset:18432
	ds_read_b128 v[176:179], v219 offset:19456
	ds_read_b128 v[188:191], v219 offset:20480
	ds_read_b128 v[198:201], v219 offset:21504
	ds_read_b128 v[202:205], v219 offset:22528
	ds_read_b128 v[206:209], v219 offset:23552
	global_load_lds_dwordx4 v[192:193], off
	s_add_i32 m0, s78, 0x2000
	s_add_u32 s82, s48, 0x40000
	v_lshl_add_u64 v[210:211], s[48:49], 0, v[180:181]
	s_addc_u32 s83, s49, 0
	s_add_i32 s78, s79, s14
	global_load_lds_dwordx4 v[210:211], off
	v_lshl_add_u64 v[212:213], s[82:83], 0, v[2:3]
	s_mov_b32 m0, s78
	v_lshl_add_u64 v[228:229], s[92:93], 0, v[180:181]
	global_load_lds_dwordx4 v[212:213], off
	v_lshl_add_u64 v[212:213], s[82:83], 0, v[180:181]
	s_add_i32 m0, s78, 0x2000
	s_nop 0
	global_load_lds_dwordx4 v[212:213], off
	v_lshl_add_u64 v[212:213], s[92:93], 0, v[2:3]
	s_mov_b32 m0, s20
	s_nop 0
	global_load_lds_dwordx4 v[212:213], off
	s_mov_b32 m0, s21
	s_nop 0
	global_load_lds_dwordx4 v[228:229], off
	s_waitcnt vmcnt(8)
	s_waitcnt lgkmcnt(0)
	s_barrier
; #define PG8_STAGE(bufoff, gbase, voff) do { _Pragma("unroll") for (int _i = 0; _i < 2; ++_i) \
;         __builtin_amdgcn_global_load_lds((const unsigned*)((const char*)(gbase) + (voff)[_i]), (PG8_LAS unsigned*)(lds + (bufoff) + ldsw + _i * 8192), 16, 0, 0); } while (0)
; #define PG8_LDA(dst, b, h) do { _Pragma("unroll") for (int m = 0; m < 4; ++m) _Pragma("unroll") for (int k = 0; k < 2; ++k) dst[m][k] = *(const PG8_LAS bf16x8*)(lds + PG8_SA(b, h) + aoff + m * 2048 + k * 1024); } while (0)
; #define PG8_LDB(dst, b, h) do { _Pragma("unroll") for (int n = 0; n < 2; ++n) _Pragma("unroll") for (int k = 0; k < 2; ++k) dst[n][k] = *(const PG8_LAS bf16x8*)(lds + PG8_SB(b, h) + boff + n * 2048 + k * 1024); } while (0)
; #define PG8_MMA(ai, bj, At, Bt) do { __builtin_amdgcn_s_setprio(1); _Pragma("unroll") for (int m = 0; m < 4; ++m) _Pragma("unroll") for (int n = 0; n < 2; ++n) _Pragma("unroll") for (int k = 0; k < 2; ++k) \
;         acc[ai][bj][m][n] = __builtin_amdgcn_mfma_f32_16x16x32_bf16(Bt[n][k], At[m][k], acc[ai][bj][m][n], 0, 0, 0); __builtin_amdgcn_s_setprio(0); } while (0)
; #define PG8_WAIT_V(n) asm volatile("s_waitcnt vmcnt(" #n ")" ::: "memory")
; #define PG8_WAIT_L(n) asm volatile("s_waitcnt lgkmcnt(" #n ")" ::: "memory")
; #define PG8_BAR __builtin_amdgcn_s_barrier()
; #define PG8_SCHED __builtin_amdgcn_sched_barrier(0)
; template <class Epi, class Sched, bool ALIGN_EPI = false, bool SP2 = false>
; __device__ __forceinline__ void gemm_phase(PG8_LAS unsigned char* lds, const Gemm g, const Sched& S, const Epi& E) {
;     ...
;             PG8_WAIT_V(8); PG8_WAIT_L(0); PG8_BAR; PG8_MMA(1, 0, At, B0); PG8_MMA(1, 1, At, B1); PG8_BAR; PG8_SCHED;
;             PG8_LDB(B0, 1, 0); PG8_LDB(B1, 1, 1); PG8_SCHED; PG8_LDA(At, 1, 0); PG8_STAGE(PG8_SA(0, 1), a2 + hstep, voffA);
;             PG8_WAIT_V(8); PG8_WAIT_L(0); PG8_BAR; PG8_MMA(0, 0, At, B0); PG8_MMA(0, 1, At, B1); PG8_BAR; PG8_SCHED;
	s_setprio 1
	s_waitcnt lgkmcnt(0)
	v_mfma_f32_16x16x32_bf16 v[64:67], v[132:135], v[164:167], v[64:67]
	v_mfma_f32_16x16x32_bf16 v[60:63], v[140:143], v[164:167], v[60:63]
	v_mfma_f32_16x16x32_bf16 v[48:51], v[132:135], v[172:175], v[48:51]
	v_mfma_f32_16x16x32_bf16 v[44:47], v[140:143], v[172:175], v[44:47]
	v_mfma_f32_16x16x32_bf16 v[32:35], v[132:135], v[188:191], v[32:35]
	v_mfma_f32_16x16x32_bf16 v[28:31], v[140:143], v[188:191], v[28:31]
	v_mfma_f32_16x16x32_bf16 v[16:19], v[132:135], v[202:205], v[16:19]
	v_mfma_f32_16x16x32_bf16 v[12:15], v[140:143], v[202:205], v[12:15]
	v_mfma_f32_16x16x32_bf16 v[64:67], v[136:139], v[168:171], v[64:67]
	v_mfma_f32_16x16x32_bf16 v[60:63], v[144:147], v[168:171], v[60:63]
	v_mfma_f32_16x16x32_bf16 v[48:51], v[136:139], v[176:179], v[48:51]
	v_mfma_f32_16x16x32_bf16 v[44:47], v[144:147], v[176:179], v[44:47]
	v_mfma_f32_16x16x32_bf16 v[32:35], v[136:139], v[198:201], v[32:35]
	v_mfma_f32_16x16x32_bf16 v[28:31], v[144:147], v[198:201], v[28:31]
	v_mfma_f32_16x16x32_bf16 v[16:19], v[136:139], v[206:209], v[16:19]
	v_mfma_f32_16x16x32_bf16 v[12:15], v[144:147], v[206:209], v[12:15]
	s_setprio 0
	s_setprio 1
	v_mfma_f32_16x16x32_bf16 v[56:59], v[148:151], v[164:167], v[56:59]
	v_mfma_f32_16x16x32_bf16 v[52:55], v[156:159], v[164:167], v[52:55]
	v_mfma_f32_16x16x32_bf16 v[40:43], v[148:151], v[172:175], v[40:43]
	v_mfma_f32_16x16x32_bf16 v[36:39], v[156:159], v[172:175], v[36:39]
	v_mfma_f32_16x16x32_bf16 v[24:27], v[148:151], v[188:191], v[24:27]
	v_mfma_f32_16x16x32_bf16 v[20:23], v[156:159], v[188:191], v[20:23]
	v_mfma_f32_16x16x32_bf16 v[8:11], v[148:151], v[202:205], v[8:11]
	v_mfma_f32_16x16x32_bf16 v[4:7], v[156:159], v[202:205], v[4:7]
	v_mfma_f32_16x16x32_bf16 v[56:59], v[152:155], v[168:171], v[56:59]
	v_mfma_f32_16x16x32_bf16 v[52:55], v[160:163], v[168:171], v[52:55]
	v_mfma_f32_16x16x32_bf16 v[40:43], v[152:155], v[176:179], v[40:43]
	v_mfma_f32_16x16x32_bf16 v[36:39], v[160:163], v[176:179], v[36:39]
	v_mfma_f32_16x16x32_bf16 v[24:27], v[152:155], v[198:201], v[24:27]
	v_mfma_f32_16x16x32_bf16 v[20:23], v[160:163], v[198:201], v[20:23]
	s_setprio 2
	s_barrier
	v_mfma_f32_16x16x32_bf16 v[8:11], v[152:155], v[206:209], v[8:11]
	v_mfma_f32_16x16x32_bf16 v[4:7], v[160:163], v[206:209], v[4:7]
	s_setprio 0
	s_add_i32 s78, 0, 0x18000
	s_add_i32 s79, 0, 0x1c000
	v_add_u32_e32 v144, s78, v214
	v_add_u32_e32 v160, s79, v214
	ds_read_b128 v[132:135], v144
	ds_read_b128 v[136:139], v144 offset:1024
	ds_read_b128 v[140:143], v144 offset:2048
	ds_read_b128 v[144:147], v144 offset:3072
	ds_read_b128 v[148:151], v160
	ds_read_b128 v[152:155], v160 offset:1024
	ds_read_b128 v[156:159], v160 offset:2048
	ds_read_b128 v[160:163], v160 offset:3072
	s_add_u32 s82, s92, 0x40000
	s_addc_u32 s83, s93, 0
	s_mov_b32 m0, s28
	v_lshl_add_u64 v[230:231], s[82:83], 0, v[2:3]
	ds_read_b128 v[164:167], v219 offset:32768
	ds_read_b128 v[168:171], v219 offset:33792
	ds_read_b128 v[172:175], v219 offset:34816
	ds_read_b128 v[176:179], v219 offset:35840
	ds_read_b128 v[188:191], v219 offset:36864
	ds_read_b128 v[198:201], v219 offset:37888
	ds_read_b128 v[202:205], v219 offset:38912
	ds_read_b128 v[206:209], v219 offset:39936
	global_load_lds_dwordx4 v[230:231], off
	v_lshl_add_u64 v[230:231], s[82:83], 0, v[180:181]
	s_mov_b32 m0, s29
	s_nop 0
	global_load_lds_dwordx4 v[230:231], off
	s_waitcnt vmcnt(8)
	s_waitcnt lgkmcnt(0)
	s_barrier
	s_setprio 1
	s_waitcnt lgkmcnt(0)
	v_mfma_f32_16x16x32_bf16 v[68:71], v[132:135], v[164:167], v[68:71]
	v_mfma_f32_16x16x32_bf16 v[72:75], v[140:143], v[164:167], v[72:75]
	v_mfma_f32_16x16x32_bf16 v[84:87], v[132:135], v[172:175], v[84:87]
	v_mfma_f32_16x16x32_bf16 v[88:91], v[140:143], v[172:175], v[88:91]
	v_mfma_f32_16x16x32_bf16 v[116:119], v[132:135], v[188:191], v[116:119]
	v_mfma_f32_16x16x32_bf16 v[124:127], v[140:143], v[188:191], v[124:127]
	v_mfma_f32_16x16x32_bf16 v[128:131], v[132:135], v[202:205], v[128:131]
	v_mfma_f32_16x16x32_bf16 v[120:123], v[140:143], v[202:205], v[120:123]
	v_mfma_f32_16x16x32_bf16 v[68:71], v[136:139], v[168:171], v[68:71]
	v_mfma_f32_16x16x32_bf16 v[72:75], v[144:147], v[168:171], v[72:75]
	v_mfma_f32_16x16x32_bf16 v[84:87], v[136:139], v[176:179], v[84:87]
	v_mfma_f32_16x16x32_bf16 v[88:91], v[144:147], v[176:179], v[88:91]
	v_mfma_f32_16x16x32_bf16 v[116:119], v[136:139], v[198:201], v[116:119]
	v_mfma_f32_16x16x32_bf16 v[124:127], v[144:147], v[198:201], v[124:127]
	v_mfma_f32_16x16x32_bf16 v[128:131], v[136:139], v[206:209], v[128:131]
	v_mfma_f32_16x16x32_bf16 v[120:123], v[144:147], v[206:209], v[120:123]
	s_setprio 0
	s_setprio 1
	v_mfma_f32_16x16x32_bf16 v[76:79], v[148:151], v[164:167], v[76:79]
	v_mfma_f32_16x16x32_bf16 v[80:83], v[156:159], v[164:167], v[80:83]
	v_mfma_f32_16x16x32_bf16 v[96:99], v[148:151], v[172:175], v[96:99]
	v_mfma_f32_16x16x32_bf16 v[100:103], v[156:159], v[172:175], v[100:103]
	v_mfma_f32_16x16x32_bf16 v[108:111], v[148:151], v[188:191], v[108:111]
	v_mfma_f32_16x16x32_bf16 v[112:115], v[156:159], v[188:191], v[112:115]
	v_mfma_f32_16x16x32_bf16 v[104:107], v[148:151], v[202:205], v[104:107]
	v_mfma_f32_16x16x32_bf16 v[92:95], v[156:159], v[202:205], v[92:95]
	v_mfma_f32_16x16x32_bf16 v[76:79], v[152:155], v[168:171], v[76:79]
	v_mfma_f32_16x16x32_bf16 v[80:83], v[160:163], v[168:171], v[80:83]
	v_mfma_f32_16x16x32_bf16 v[96:99], v[152:155], v[176:179], v[96:99]
	v_mfma_f32_16x16x32_bf16 v[100:103], v[160:163], v[176:179], v[100:103]
	v_mfma_f32_16x16x32_bf16 v[108:111], v[152:155], v[198:201], v[108:111]
	v_mfma_f32_16x16x32_bf16 v[112:115], v[160:163], v[198:201], v[112:115]
	s_setprio 2
	s_barrier
; #define PG8_STAGE(bufoff, gbase, voff) do { _Pragma("unroll") for (int _i = 0; _i < 2; ++_i) \
;         __builtin_amdgcn_global_load_lds((const unsigned*)((const char*)(gbase) + (voff)[_i]), (PG8_LAS unsigned*)(lds + (bufoff) + ldsw + _i * 8192), 16, 0, 0); } while (0)
; #define PG8_LDA(dst, b, h) do { _Pragma("unroll") for (int m = 0; m < 4; ++m) _Pragma("unroll") for (int k = 0; k < 2; ++k) dst[m][k] = *(const PG8_LAS bf16x8*)(lds + PG8_SA(b, h) + aoff + m * 2048 + k * 1024); } while (0)
; #define PG8_MMA(ai, bj, At, Bt) do { __builtin_amdgcn_s_setprio(1); _Pragma("unroll") for (int m = 0; m < 4; ++m) _Pragma("unroll") for (int n = 0; n < 2; ++n) _Pragma("unroll") for (int k = 0; k < 2; ++k) \
;         acc[ai][bj][m][n] = __builtin_amdgcn_mfma_f32_16x16x32_bf16(Bt[n][k], At[m][k], acc[ai][bj][m][n], 0, 0, 0); __builtin_amdgcn_s_setprio(0); } while (0)
; #define PG8_WAIT_V(n) asm volatile("s_waitcnt vmcnt(" #n ")" ::: "memory")
; #define PG8_WAIT_L(n) asm volatile("s_waitcnt lgkmcnt(" #n ")" ::: "memory")
; #define PG8_BAR __builtin_amdgcn_s_barrier()
; #define PG8_SCHED __builtin_amdgcn_sched_barrier(0)
; template <class Epi, class Sched, bool ALIGN_EPI = false, bool SP2 = false>
; __device__ __forceinline__ void gemm_phase(PG8_LAS unsigned char* lds, const Gemm g, const Sched& S, const Epi& E) {
;     ...
;             PG8_LDA(At, 1, 1); PG8_STAGE(PG8_SB(1, 0), b3, voffB); PG8_STAGE(PG8_SB(1, 1), b3 + hstep, voffB); PG8_STAGE(PG8_SA(1, 0), a3, voffA);
;             PG8_WAIT_V(8); PG8_WAIT_L(0); PG8_BAR; PG8_MMA(1, 0, At, B0); PG8_MMA(1, 1, At, B1); PG8_BAR; PG8_SCHED;
;     ...
;         if constexpr (ALIGN_EPI) { if (wr == 0) PG8_BAR; }
	v_mfma_f32_16x16x32_bf16 v[104:107], v[152:155], v[206:209], v[104:107]
	v_mfma_f32_16x16x32_bf16 v[92:95], v[160:163], v[206:209], v[92:95]
	s_setprio 0
	s_add_i32 s78, s78, s14
	v_lshl_add_u64 v[192:193], v[192:193], 0, s[50:51]
	s_mov_b32 m0, s78
	ds_read_b128 v[164:167], v219 offset:49152
	ds_read_b128 v[168:171], v219 offset:50176
	ds_read_b128 v[172:175], v219 offset:51200
	ds_read_b128 v[176:179], v219 offset:52224
	ds_read_b128 v[188:191], v219 offset:53248
	ds_read_b128 v[198:201], v219 offset:54272
	ds_read_b128 v[202:205], v219 offset:55296
	ds_read_b128 v[206:209], v219 offset:56320
	global_load_lds_dwordx4 v[192:193], off
	s_add_i32 m0, s78, 0x2000
	s_add_u32 s48, s48, 0x40080
	v_lshl_add_u64 v[192:193], v[210:211], 0, s[50:51]
	s_addc_u32 s49, s49, 0
	s_add_i32 s78, s79, s14
	global_load_lds_dwordx4 v[192:193], off
	v_lshl_add_u64 v[192:193], s[48:49], 0, v[2:3]
	s_mov_b32 m0, s78
	s_nop 0
	global_load_lds_dwordx4 v[192:193], off
	v_lshl_add_u64 v[192:193], s[48:49], 0, v[180:181]
	s_add_i32 m0, s78, 0x2000
	s_nop 0
	global_load_lds_dwordx4 v[192:193], off
	v_lshl_add_u64 v[192:193], v[212:213], 0, s[50:51]
	s_mov_b32 m0, s30
	s_nop 0
	global_load_lds_dwordx4 v[192:193], off
	v_lshl_add_u64 v[192:193], v[228:229], 0, s[50:51]
	s_mov_b32 m0, s31
	s_nop 0
	global_load_lds_dwordx4 v[192:193], off
	s_waitcnt vmcnt(8)
	s_waitcnt lgkmcnt(0)
	s_barrier
	s_setprio 1
	s_waitcnt lgkmcnt(0)
	v_mfma_f32_16x16x32_bf16 v[64:67], v[132:135], v[164:167], v[64:67]
	v_mfma_f32_16x16x32_bf16 v[60:63], v[140:143], v[164:167], v[60:63]
	v_mfma_f32_16x16x32_bf16 v[48:51], v[132:135], v[172:175], v[48:51]
	v_mfma_f32_16x16x32_bf16 v[44:47], v[140:143], v[172:175], v[44:47]
	v_mfma_f32_16x16x32_bf16 v[32:35], v[132:135], v[188:191], v[32:35]
	v_mfma_f32_16x16x32_bf16 v[28:31], v[140:143], v[188:191], v[28:31]
	v_mfma_f32_16x16x32_bf16 v[16:19], v[132:135], v[202:205], v[16:19]
	v_mfma_f32_16x16x32_bf16 v[12:15], v[140:143], v[202:205], v[12:15]
	v_mfma_f32_16x16x32_bf16 v[64:67], v[136:139], v[168:171], v[64:67]
	v_mfma_f32_16x16x32_bf16 v[60:63], v[144:147], v[168:171], v[60:63]
	v_mfma_f32_16x16x32_bf16 v[48:51], v[136:139], v[176:179], v[48:51]
	v_mfma_f32_16x16x32_bf16 v[44:47], v[144:147], v[176:179], v[44:47]
	v_mfma_f32_16x16x32_bf16 v[32:35], v[136:139], v[198:201], v[32:35]
	v_mfma_f32_16x16x32_bf16 v[28:31], v[144:147], v[198:201], v[28:31]
	v_mfma_f32_16x16x32_bf16 v[16:19], v[136:139], v[206:209], v[16:19]
	v_mfma_f32_16x16x32_bf16 v[12:15], v[144:147], v[206:209], v[12:15]
	s_setprio 0
	s_setprio 1
	v_mfma_f32_16x16x32_bf16 v[56:59], v[148:151], v[164:167], v[56:59]
	v_mfma_f32_16x16x32_bf16 v[52:55], v[156:159], v[164:167], v[52:55]
	v_mfma_f32_16x16x32_bf16 v[40:43], v[148:151], v[172:175], v[40:43]
	v_mfma_f32_16x16x32_bf16 v[36:39], v[156:159], v[172:175], v[36:39]
	v_mfma_f32_16x16x32_bf16 v[24:27], v[148:151], v[188:191], v[24:27]
	v_mfma_f32_16x16x32_bf16 v[20:23], v[156:159], v[188:191], v[20:23]
	v_mfma_f32_16x16x32_bf16 v[8:11], v[148:151], v[202:205], v[8:11]
	v_mfma_f32_16x16x32_bf16 v[4:7], v[156:159], v[202:205], v[4:7]
	v_mfma_f32_16x16x32_bf16 v[56:59], v[152:155], v[168:171], v[56:59]
	v_mfma_f32_16x16x32_bf16 v[52:55], v[160:163], v[168:171], v[52:55]
	v_mfma_f32_16x16x32_bf16 v[40:43], v[152:155], v[176:179], v[40:43]
	v_mfma_f32_16x16x32_bf16 v[36:39], v[160:163], v[176:179], v[36:39]
	v_mfma_f32_16x16x32_bf16 v[24:27], v[152:155], v[198:201], v[24:27]
	v_mfma_f32_16x16x32_bf16 v[20:23], v[160:163], v[198:201], v[20:23]
	s_setprio 2
	s_barrier
	v_mfma_f32_16x16x32_bf16 v[8:11], v[152:155], v[206:209], v[8:11]
	v_mfma_f32_16x16x32_bf16 v[4:7], v[160:163], v[206:209], v[4:7]
	s_setprio 0
	s_add_i32 s77, s77, 2
	s_add_u32 s80, s80, 0x100
	s_addc_u32 s81, s81, 0
	s_add_u32 s37, s37, 0x100
	s_addc_u32 s76, s76, 0
	s_cmp_gt_u32 s77, 13
	s_cbranch_scc0 .LBB0_783
	s_and_b64 vcc, exec, s[6:7]
	s_cbranch_vccz .LBB0_786
	s_barrier
